# stack on top: EpiUp fmaxf input canonicalisations folded away, diffmix row reductions via DPP/permlane swaps instead of serialized ds_swizzle rungs (bit-identical sums), static prio for waves 4-7 in t
# baseline (speedup 1.0000x reference)
; __device__ __forceinline__ void st_bf8(bf16* p, f32x4 a, f32x4 b) { u32x4 w; w.x = pk2(a[0], a[1]); w.y = pk2(a[2], a[3]); w.z = pk2(b[0], b[1]); w.w = pk2(b[2], b[3]); *(u32x4*)p = w; }
;     __device__ __forceinline__ void operator()(AccRef acc, const pg8::Unit& u, int wr, int wc, int fr, int fq) const {
;         const int c0 = u.pn * 256;
; #pragma unroll
;         for (int ai = 0; ai < 2; ++ai)
; #pragma unroll
;             for (int m = 0; m < 4; ++m) {
;                 const int row = u.pm * 256 + ai * 128 + wr * 64 + m * 16 + fr; const size_t rw = (size_t)row;
;                 const float rs2 = 1.0f / (SSQ[row] * (1.f / 1024.f) + EPSN);
; #pragma unroll
;                 for (int bj = 0; bj < 2; ++bj) {
;                     const int cl = bj * 128 + wc * 32 + 8 * fq; const f32x4 v0 = acc[ai][bj][m][0], v1 = acc[ai][bj][m][1];
;                     f32x4 r0, r1; r0[0] = fmaxf(v0[0], 0.f); r0[1] = fmaxf(v0[1], 0.f); r0[2] = fmaxf(v0[2], 0.f); r0[3] = fmaxf(v0[3], 0.f); r1[0] = fmaxf(v1[0], 0.f); r1[1] = fmaxf(v1[1], 0.f); r1[2] = fmaxf(v1[2], 0.f); r1[3] = fmaxf(v1[3], 0.f);
;                     st_bf8(U + rw * 4096 + c0 + cl, r0 * r0 * rs2, r1 * r1 * rs2);
;                 }
;                 asm volatile("" ::: "memory");
;             }
;     }
.LBB0_333:
	v_lshl_add_u32 v140, s57, 8, v145
	v_ashrrev_i32_e32 v141, 31, v140
	v_lshl_add_u64 v[142:143], v[140:141], 2, s[18:19]
	global_load_dword v160, v[142:143], off
	global_load_dword v161, v[142:143], off offset:64
	global_load_dword v162, v[142:143], off offset:128
	global_load_dword v163, v[142:143], off offset:192
	global_load_dword v164, v[142:143], off offset:512
	global_load_dword v165, v[142:143], off offset:576
	global_load_dword v166, v[142:143], off offset:640
	global_load_dword v167, v[142:143], off offset:704
	v_max_f32_e32 v148, v116, v116
	v_max_f32_e32 v149, v117, v117
	v_max_f32_e32 v116, 0, v120
	v_max_f32_e32 v117, 0, v121
	v_max_f32_e32 v120, 0, v148
	v_max_f32_e32 v121, 0, v149
	v_lshlrev_b64 v[148:149], 13, v[140:141]
	v_max_f32_e32 v151, v118, v118
	v_max_f32_e32 v118, 0, v122
	v_max_f32_e32 v122, 0, v151
	v_max_f32_e32 v153, v112, v112
	v_max_f32_e32 v152, v119, v119
	v_max_f32_e32 v112, 0, v124
	v_max_f32_e32 v124, 0, v153
	v_max_f32_e32 v119, 0, v123
	v_max_f32_e32 v123, 0, v152
	v_max_f32_e32 v154, v113, v113
	v_max_f32_e32 v113, 0, v125
	v_max_f32_e32 v125, 0, v154
	s_lshl_b32 s26, s58, 8
	v_max_f32_e32 v155, v114, v114
	v_max_f32_e32 v156, v115, v115
	s_ashr_i32 s27, s26, 31
	v_max_f32_e32 v114, 0, v126
	v_max_f32_e32 v115, 0, v127
	v_max_f32_e32 v126, 0, v155
	v_max_f32_e32 v127, 0, v156
	s_lshl_b64 s[26:27], s[26:27], 1
	v_pk_mul_f32 v[112:113], v[112:113], v[112:113]
	v_pk_mul_f32 v[114:115], v[114:115], v[114:115]
	v_pk_mul_f32 v[116:117], v[116:117], v[116:117]
	v_pk_mul_f32 v[118:119], v[118:119], v[118:119]
	v_lshl_add_u64 v[148:149], s[10:11], 0, v[148:149]
	v_pk_mul_f32 v[120:121], v[120:121], v[120:121]
	v_pk_mul_f32 v[122:123], v[122:123], v[122:123]
	v_pk_mul_f32 v[124:125], v[124:125], v[124:125]
	v_pk_mul_f32 v[126:127], v[126:127], v[126:127]
	v_lshl_add_u64 v[148:149], v[148:149], 0, s[26:27]
	v_lshl_add_u64 v[148:149], v[148:149], 0, v[184:185]
	s_waitcnt vmcnt(7)
	v_fmamk_f32 v141, v160, 0x3a800000, v205
	v_rcp_f32_e32 v150, v141
	s_nop 0
	v_pk_mul_f32 v[114:115], v[114:115], v[150:151] op_sel_hi:[1,0]
	v_pk_mul_f32 v[112:113], v[112:113], v[150:151] op_sel_hi:[1,0]
	v_pk_mul_f32 v[118:119], v[118:119], v[150:151] op_sel_hi:[1,0]
	v_pk_mul_f32 v[116:117], v[116:117], v[150:151] op_sel_hi:[1,0]
	v_pk_mul_f32 v[122:123], v[122:123], v[150:151] op_sel_hi:[1,0]
	v_pk_mul_f32 v[120:121], v[120:121], v[150:151] op_sel_hi:[1,0]
	v_pk_mul_f32 v[126:127], v[126:127], v[150:151] op_sel_hi:[1,0]
	v_pk_mul_f32 v[124:125], v[124:125], v[150:151] op_sel_hi:[1,0]
	v_cvt_pk_bf16_f32 v112, v112, v113
	v_cvt_pk_bf16_f32 v113, v114, v115
	v_cvt_pk_bf16_f32 v114, v116, v117
	v_cvt_pk_bf16_f32 v115, v118, v119
	v_cvt_pk_bf16_f32 v116, v120, v121
	v_cvt_pk_bf16_f32 v117, v122, v123
	v_cvt_pk_bf16_f32 v118, v124, v125
	v_cvt_pk_bf16_f32 v119, v126, v127
	global_store_dwordx4 v[148:149], v[112:115], off
	global_store_dwordx4 v[148:149], v[116:119], off offset:256
	s_nop 1
	v_max_f32_e32 v112, v100, v100
	v_max_f32_e32 v117, v96, v96
	v_max_f32_e32 v119, v99, v99
	v_max_f32_e32 v99, 0, v109
	v_max_f32_e32 v109, 0, v103
	v_or_b32_e32 v96, 16, v140
	v_max_f32_e32 v100, 0, v110
	v_max_f32_e32 v110, 0, v117
	v_max_f32_e32 v113, v101, v101
	v_max_f32_e32 v115, v102, v102
	v_max_f32_e32 v101, 0, v111
	v_max_f32_e32 v102, 0, v104
	v_max_f32_e32 v104, 0, v106
	v_max_f32_e32 v106, 0, v112
	v_max_f32_e32 v111, 0, v97
	v_max_f32_e32 v112, 0, v98
	v_ashrrev_i32_e32 v97, 31, v96
	v_lshlrev_b64 v[96:97], 13, v[96:97]
	v_lshl_add_u64 v[96:97], s[10:11], 0, v[96:97]
	v_lshl_add_u64 v[96:97], v[96:97], 0, s[26:27]
	v_max_f32_e32 v98, 0, v108
	v_max_f32_e32 v108, 0, v115
	v_max_f32_e32 v103, 0, v105
	v_max_f32_e32 v105, 0, v107
	v_max_f32_e32 v107, 0, v113
	v_max_f32_e32 v113, 0, v119
	v_pk_mul_f32 v[98:99], v[98:99], v[98:99]
	v_pk_mul_f32 v[100:101], v[100:101], v[100:101]
	v_pk_mul_f32 v[102:103], v[102:103], v[102:103]
	v_pk_mul_f32 v[104:105], v[104:105], v[104:105]
	v_pk_mul_f32 v[106:107], v[106:107], v[106:107]
	v_pk_mul_f32 v[108:109], v[108:109], v[108:109]
	v_pk_mul_f32 v[110:111], v[110:111], v[110:111]
	v_pk_mul_f32 v[112:113], v[112:113], v[112:113]
	s_waitcnt vmcnt(8)
	v_fmamk_f32 v116, v161, 0x3a800000, v205
	v_lshl_add_u64 v[114:115], v[96:97], 0, v[184:185]
	v_rcp_f32_e32 v96, v116
	s_nop 0
	v_pk_mul_f32 v[100:101], v[100:101], v[96:97] op_sel_hi:[1,0]
	v_pk_mul_f32 v[98:99], v[98:99], v[96:97] op_sel_hi:[1,0]
	v_pk_mul_f32 v[104:105], v[104:105], v[96:97] op_sel_hi:[1,0]
	v_pk_mul_f32 v[102:103], v[102:103], v[96:97] op_sel_hi:[1,0]
	v_pk_mul_f32 v[108:109], v[108:109], v[96:97] op_sel_hi:[1,0]
	v_pk_mul_f32 v[106:107], v[106:107], v[96:97] op_sel_hi:[1,0]
	v_pk_mul_f32 v[112:113], v[112:113], v[96:97] op_sel_hi:[1,0]
	v_pk_mul_f32 v[110:111], v[110:111], v[96:97] op_sel_hi:[1,0]
	v_cvt_pk_bf16_f32 v96, v98, v99
	v_cvt_pk_bf16_f32 v97, v100, v101
	v_cvt_pk_bf16_f32 v98, v102, v103
	v_cvt_pk_bf16_f32 v99, v104, v105
	v_cvt_pk_bf16_f32 v100, v106, v107
	v_cvt_pk_bf16_f32 v101, v108, v109
	v_cvt_pk_bf16_f32 v102, v110, v111
	v_cvt_pk_bf16_f32 v103, v112, v113
	global_store_dwordx4 v[114:115], v[96:99], off
	global_store_dwordx4 v[114:115], v[100:103], off offset:256
	s_nop 1
	v_max_f32_e32 v96, v84, v84
	v_max_f32_e32 v101, v80, v80
	v_max_f32_e32 v103, v83, v83
	v_max_f32_e32 v83, 0, v93
	v_max_f32_e32 v93, 0, v87
	v_or_b32_e32 v80, 32, v140
	v_max_f32_e32 v84, 0, v94
	v_max_f32_e32 v94, 0, v101
	v_max_f32_e32 v97, v85, v85
	v_max_f32_e32 v99, v86, v86
	v_max_f32_e32 v85, 0, v95
	v_max_f32_e32 v86, 0, v88
	v_max_f32_e32 v88, 0, v90
	v_max_f32_e32 v90, 0, v96
	v_max_f32_e32 v95, 0, v81
	v_max_f32_e32 v96, 0, v82
	v_ashrrev_i32_e32 v81, 31, v80
	v_lshlrev_b64 v[80:81], 13, v[80:81]
	v_lshl_add_u64 v[80:81], s[10:11], 0, v[80:81]
	v_lshl_add_u64 v[80:81], v[80:81], 0, s[26:27]
	v_max_f32_e32 v82, 0, v92
	v_max_f32_e32 v92, 0, v99
	v_max_f32_e32 v87, 0, v89
	v_max_f32_e32 v89, 0, v91
	v_max_f32_e32 v91, 0, v97
	v_max_f32_e32 v97, 0, v103
	v_pk_mul_f32 v[82:83], v[82:83], v[82:83]
	v_pk_mul_f32 v[84:85], v[84:85], v[84:85]
	v_pk_mul_f32 v[86:87], v[86:87], v[86:87]
	v_pk_mul_f32 v[88:89], v[88:89], v[88:89]
	v_pk_mul_f32 v[90:91], v[90:91], v[90:91]
	v_pk_mul_f32 v[92:93], v[92:93], v[92:93]
	v_pk_mul_f32 v[94:95], v[94:95], v[94:95]
	v_pk_mul_f32 v[96:97], v[96:97], v[96:97]
	s_waitcnt vmcnt(9)
; __device__ __forceinline__ void st_bf8(bf16* p, f32x4 a, f32x4 b) { u32x4 w; w.x = pk2(a[0], a[1]); w.y = pk2(a[2], a[3]); w.z = pk2(b[0], b[1]); w.w = pk2(b[2], b[3]); *(u32x4*)p = w; }
;     __device__ __forceinline__ void operator()(AccRef acc, const pg8::Unit& u, int wr, int wc, int fr, int fq) const {
;         const int c0 = u.pn * 256;
; #pragma unroll
;         for (int ai = 0; ai < 2; ++ai)
; #pragma unroll
;             for (int m = 0; m < 4; ++m) {
;                 const int row = u.pm * 256 + ai * 128 + wr * 64 + m * 16 + fr; const size_t rw = (size_t)row;
;                 const float rs2 = 1.0f / (SSQ[row] * (1.f / 1024.f) + EPSN);
; #pragma unroll
;                 for (int bj = 0; bj < 2; ++bj) {
;                     const int cl = bj * 128 + wc * 32 + 8 * fq; const f32x4 v0 = acc[ai][bj][m][0], v1 = acc[ai][bj][m][1];
;                     f32x4 r0, r1; r0[0] = fmaxf(v0[0], 0.f); r0[1] = fmaxf(v0[1], 0.f); r0[2] = fmaxf(v0[2], 0.f); r0[3] = fmaxf(v0[3], 0.f); r1[0] = fmaxf(v1[0], 0.f); r1[1] = fmaxf(v1[1], 0.f); r1[2] = fmaxf(v1[2], 0.f); r1[3] = fmaxf(v1[3], 0.f);
;                     st_bf8(U + rw * 4096 + c0 + cl, r0 * r0 * rs2, r1 * r1 * rs2);
;                 }
;                 asm volatile("" ::: "memory");
;             }
;     }
	v_fmamk_f32 v100, v162, 0x3a800000, v205
	v_lshl_add_u64 v[98:99], v[80:81], 0, v[184:185]
	v_rcp_f32_e32 v80, v100
	s_nop 0
	v_pk_mul_f32 v[84:85], v[84:85], v[80:81] op_sel_hi:[1,0]
	v_pk_mul_f32 v[82:83], v[82:83], v[80:81] op_sel_hi:[1,0]
	v_pk_mul_f32 v[88:89], v[88:89], v[80:81] op_sel_hi:[1,0]
	v_pk_mul_f32 v[86:87], v[86:87], v[80:81] op_sel_hi:[1,0]
	v_pk_mul_f32 v[92:93], v[92:93], v[80:81] op_sel_hi:[1,0]
	v_pk_mul_f32 v[90:91], v[90:91], v[80:81] op_sel_hi:[1,0]
	v_pk_mul_f32 v[96:97], v[96:97], v[80:81] op_sel_hi:[1,0]
	v_pk_mul_f32 v[94:95], v[94:95], v[80:81] op_sel_hi:[1,0]
	v_cvt_pk_bf16_f32 v80, v82, v83
	v_cvt_pk_bf16_f32 v81, v84, v85
	v_cvt_pk_bf16_f32 v82, v86, v87
	v_cvt_pk_bf16_f32 v83, v88, v89
	v_cvt_pk_bf16_f32 v84, v90, v91
	v_cvt_pk_bf16_f32 v85, v92, v93
	v_cvt_pk_bf16_f32 v86, v94, v95
	v_cvt_pk_bf16_f32 v87, v96, v97
	global_store_dwordx4 v[98:99], v[80:83], off
	global_store_dwordx4 v[98:99], v[84:87], off offset:256
	s_nop 1
	v_max_f32_e32 v80, v68, v68
	v_max_f32_e32 v85, v64, v64
	v_max_f32_e32 v87, v67, v67
	v_max_f32_e32 v67, 0, v77
	v_max_f32_e32 v77, 0, v71
	v_or_b32_e32 v64, 48, v140
	v_max_f32_e32 v68, 0, v78
	v_max_f32_e32 v78, 0, v85
	v_max_f32_e32 v81, v69, v69
	v_max_f32_e32 v83, v70, v70
	v_max_f32_e32 v69, 0, v79
	v_max_f32_e32 v70, 0, v72
	v_max_f32_e32 v72, 0, v74
	v_max_f32_e32 v74, 0, v80
	v_max_f32_e32 v79, 0, v65
	v_max_f32_e32 v80, 0, v66
	v_ashrrev_i32_e32 v65, 31, v64
	v_lshlrev_b64 v[64:65], 13, v[64:65]
	v_lshl_add_u64 v[64:65], s[10:11], 0, v[64:65]
	v_lshl_add_u64 v[64:65], v[64:65], 0, s[26:27]
	v_max_f32_e32 v66, 0, v76
	v_max_f32_e32 v76, 0, v83
	v_max_f32_e32 v71, 0, v73
	v_max_f32_e32 v73, 0, v75
	v_max_f32_e32 v75, 0, v81
	v_max_f32_e32 v81, 0, v87
	v_pk_mul_f32 v[66:67], v[66:67], v[66:67]
	v_pk_mul_f32 v[68:69], v[68:69], v[68:69]
	v_pk_mul_f32 v[70:71], v[70:71], v[70:71]
	v_pk_mul_f32 v[72:73], v[72:73], v[72:73]
	v_pk_mul_f32 v[74:75], v[74:75], v[74:75]
	v_pk_mul_f32 v[76:77], v[76:77], v[76:77]
	v_pk_mul_f32 v[78:79], v[78:79], v[78:79]
	v_pk_mul_f32 v[80:81], v[80:81], v[80:81]
	s_waitcnt vmcnt(10)
	v_fmamk_f32 v84, v163, 0x3a800000, v205
	v_lshl_add_u64 v[82:83], v[64:65], 0, v[184:185]
	v_rcp_f32_e32 v64, v84
	s_nop 0
	v_pk_mul_f32 v[68:69], v[68:69], v[64:65] op_sel_hi:[1,0]
	v_pk_mul_f32 v[66:67], v[66:67], v[64:65] op_sel_hi:[1,0]
	v_pk_mul_f32 v[72:73], v[72:73], v[64:65] op_sel_hi:[1,0]
	v_pk_mul_f32 v[70:71], v[70:71], v[64:65] op_sel_hi:[1,0]
	v_pk_mul_f32 v[76:77], v[76:77], v[64:65] op_sel_hi:[1,0]
	v_pk_mul_f32 v[74:75], v[74:75], v[64:65] op_sel_hi:[1,0]
	v_pk_mul_f32 v[80:81], v[80:81], v[64:65] op_sel_hi:[1,0]
	v_pk_mul_f32 v[78:79], v[78:79], v[64:65] op_sel_hi:[1,0]
	v_cvt_pk_bf16_f32 v64, v66, v67
	v_cvt_pk_bf16_f32 v65, v68, v69
	v_cvt_pk_bf16_f32 v66, v70, v71
	v_cvt_pk_bf16_f32 v67, v72, v73
	v_cvt_pk_bf16_f32 v68, v74, v75
	v_cvt_pk_bf16_f32 v69, v76, v77
	v_cvt_pk_bf16_f32 v70, v78, v79
	v_cvt_pk_bf16_f32 v71, v80, v81
	global_store_dwordx4 v[82:83], v[64:67], off
	global_store_dwordx4 v[82:83], v[68:71], off offset:256
	s_nop 1
	v_max_f32_e32 v64, v52, v52
	v_max_f32_e32 v69, v48, v48
	v_max_f32_e32 v71, v51, v51
	v_max_f32_e32 v51, 0, v61
	v_max_f32_e32 v61, 0, v55
	v_add_u32_e32 v48, 0x80, v140
	v_max_f32_e32 v52, 0, v62
	v_max_f32_e32 v62, 0, v69
	v_max_f32_e32 v65, v53, v53
	v_max_f32_e32 v67, v54, v54
	v_max_f32_e32 v53, 0, v63
	v_max_f32_e32 v54, 0, v56
	v_max_f32_e32 v56, 0, v58
	v_max_f32_e32 v58, 0, v64
	v_max_f32_e32 v63, 0, v49
	v_max_f32_e32 v64, 0, v50
	v_ashrrev_i32_e32 v49, 31, v48
	v_lshlrev_b64 v[48:49], 13, v[48:49]
	v_lshl_add_u64 v[48:49], s[10:11], 0, v[48:49]
	v_lshl_add_u64 v[48:49], v[48:49], 0, s[26:27]
	v_max_f32_e32 v50, 0, v60
	v_max_f32_e32 v60, 0, v67
	v_max_f32_e32 v55, 0, v57
	v_max_f32_e32 v57, 0, v59
	v_max_f32_e32 v59, 0, v65
	v_max_f32_e32 v65, 0, v71
	v_pk_mul_f32 v[50:51], v[50:51], v[50:51]
	v_pk_mul_f32 v[52:53], v[52:53], v[52:53]
	v_pk_mul_f32 v[54:55], v[54:55], v[54:55]
	v_pk_mul_f32 v[56:57], v[56:57], v[56:57]
	v_pk_mul_f32 v[58:59], v[58:59], v[58:59]
	v_pk_mul_f32 v[60:61], v[60:61], v[60:61]
	v_pk_mul_f32 v[62:63], v[62:63], v[62:63]
	v_pk_mul_f32 v[64:65], v[64:65], v[64:65]
	s_waitcnt vmcnt(11)
	v_fmamk_f32 v68, v164, 0x3a800000, v205
	v_lshl_add_u64 v[66:67], v[48:49], 0, v[184:185]
	v_rcp_f32_e32 v48, v68
	s_nop 0
	v_pk_mul_f32 v[52:53], v[52:53], v[48:49] op_sel_hi:[1,0]
	v_pk_mul_f32 v[50:51], v[50:51], v[48:49] op_sel_hi:[1,0]
	v_pk_mul_f32 v[56:57], v[56:57], v[48:49] op_sel_hi:[1,0]
	v_pk_mul_f32 v[54:55], v[54:55], v[48:49] op_sel_hi:[1,0]
	v_pk_mul_f32 v[60:61], v[60:61], v[48:49] op_sel_hi:[1,0]
	v_pk_mul_f32 v[58:59], v[58:59], v[48:49] op_sel_hi:[1,0]
	v_pk_mul_f32 v[64:65], v[64:65], v[48:49] op_sel_hi:[1,0]
	v_pk_mul_f32 v[62:63], v[62:63], v[48:49] op_sel_hi:[1,0]
	v_cvt_pk_bf16_f32 v48, v50, v51
	v_cvt_pk_bf16_f32 v49, v52, v53
	v_cvt_pk_bf16_f32 v50, v54, v55
	v_cvt_pk_bf16_f32 v51, v56, v57
	v_cvt_pk_bf16_f32 v52, v58, v59
	v_cvt_pk_bf16_f32 v53, v60, v61
	v_cvt_pk_bf16_f32 v54, v62, v63
	v_cvt_pk_bf16_f32 v55, v64, v65
	global_store_dwordx4 v[66:67], v[48:51], off
	global_store_dwordx4 v[66:67], v[52:55], off offset:256
	s_nop 1
	v_max_f32_e32 v48, v36, v36
	v_max_f32_e32 v53, v32, v32
	v_max_f32_e32 v55, v35, v35
	v_max_f32_e32 v35, 0, v45
	v_max_f32_e32 v45, 0, v39
	v_add_u32_e32 v32, 0x90, v140
	v_max_f32_e32 v36, 0, v46
	v_max_f32_e32 v46, 0, v53
	v_max_f32_e32 v49, v37, v37
	v_max_f32_e32 v51, v38, v38
	v_max_f32_e32 v37, 0, v47
	v_max_f32_e32 v38, 0, v40
	v_max_f32_e32 v40, 0, v42
	v_max_f32_e32 v42, 0, v48
	v_max_f32_e32 v47, 0, v33
	v_max_f32_e32 v48, 0, v34
	v_ashrrev_i32_e32 v33, 31, v32
	v_lshlrev_b64 v[32:33], 13, v[32:33]
	v_lshl_add_u64 v[32:33], s[10:11], 0, v[32:33]
	v_lshl_add_u64 v[32:33], v[32:33], 0, s[26:27]
	v_max_f32_e32 v34, 0, v44
	v_max_f32_e32 v44, 0, v51
	v_max_f32_e32 v39, 0, v41
	v_max_f32_e32 v41, 0, v43
	v_max_f32_e32 v43, 0, v49
	v_max_f32_e32 v49, 0, v55
	v_pk_mul_f32 v[34:35], v[34:35], v[34:35]
	v_pk_mul_f32 v[36:37], v[36:37], v[36:37]
	v_pk_mul_f32 v[38:39], v[38:39], v[38:39]
	v_pk_mul_f32 v[40:41], v[40:41], v[40:41]
	v_pk_mul_f32 v[42:43], v[42:43], v[42:43]
	v_pk_mul_f32 v[44:45], v[44:45], v[44:45]
	v_pk_mul_f32 v[46:47], v[46:47], v[46:47]
	v_pk_mul_f32 v[48:49], v[48:49], v[48:49]
	s_waitcnt vmcnt(12)
; #define PG8_BAR __builtin_amdgcn_s_barrier()
; __device__ __forceinline__ void st_bf8(bf16* p, f32x4 a, f32x4 b) { u32x4 w; w.x = pk2(a[0], a[1]); w.y = pk2(a[2], a[3]); w.z = pk2(b[0], b[1]); w.w = pk2(b[2], b[3]); *(u32x4*)p = w; }
; template <class Epi, class Sched, bool ALIGN_EPI = false, bool SP2 = false>
; __device__ __forceinline__ void gemm_phase(PG8_LAS unsigned char* lds, const Gemm g, const Sched& S, const Epi& E, const int tid_in) {
;     ...
;         if (!has_next) break;
; #pragma unroll
;         for (int a = 0; a < 2; ++a)
; #pragma unroll
;             for (int b = 0; b < 2; ++b)
; #pragma unroll
;                 for (int m = 0; m < 4; ++m)
; #pragma unroll
;                     for (int n = 0; n < 2; ++n) acc[a][b][m][n] = (f32x4){0.f, 0.f, 0.f, 0.f};
;         cur = nxt; cA = nA; cB = nB; ++ui;
;         if constexpr (ALIGN_EPI) { if (wr == 1) PG8_BAR; }
;     __device__ __forceinline__ void operator()(AccRef acc, const pg8::Unit& u, int wr, int wc, int fr, int fq) const {
;         const int c0 = u.pn * 256;
; #pragma unroll
;         for (int ai = 0; ai < 2; ++ai)
; #pragma unroll
;             for (int m = 0; m < 4; ++m) {
;                 const int row = u.pm * 256 + ai * 128 + wr * 64 + m * 16 + fr; const size_t rw = (size_t)row;
;                 const float rs2 = 1.0f / (SSQ[row] * (1.f / 1024.f) + EPSN);
; #pragma unroll
;                 for (int bj = 0; bj < 2; ++bj) {
;                     const int cl = bj * 128 + wc * 32 + 8 * fq; const f32x4 v0 = acc[ai][bj][m][0], v1 = acc[ai][bj][m][1];
;                     f32x4 r0, r1; r0[0] = fmaxf(v0[0], 0.f); r0[1] = fmaxf(v0[1], 0.f); r0[2] = fmaxf(v0[2], 0.f); r0[3] = fmaxf(v0[3], 0.f); r1[0] = fmaxf(v1[0], 0.f); r1[1] = fmaxf(v1[1], 0.f); r1[2] = fmaxf(v1[2], 0.f); r1[3] = fmaxf(v1[3], 0.f);
;                     st_bf8(U + rw * 4096 + c0 + cl, r0 * r0 * rs2, r1 * r1 * rs2);
;                 }
;                 asm volatile("" ::: "memory");
;             }
;     }
	v_fmamk_f32 v52, v165, 0x3a800000, v205
	v_lshl_add_u64 v[50:51], v[32:33], 0, v[184:185]
	v_rcp_f32_e32 v32, v52
	s_nop 0
	v_pk_mul_f32 v[36:37], v[36:37], v[32:33] op_sel_hi:[1,0]
	v_pk_mul_f32 v[34:35], v[34:35], v[32:33] op_sel_hi:[1,0]
	v_pk_mul_f32 v[40:41], v[40:41], v[32:33] op_sel_hi:[1,0]
	v_pk_mul_f32 v[38:39], v[38:39], v[32:33] op_sel_hi:[1,0]
	v_pk_mul_f32 v[44:45], v[44:45], v[32:33] op_sel_hi:[1,0]
	v_pk_mul_f32 v[42:43], v[42:43], v[32:33] op_sel_hi:[1,0]
	v_pk_mul_f32 v[48:49], v[48:49], v[32:33] op_sel_hi:[1,0]
	v_pk_mul_f32 v[46:47], v[46:47], v[32:33] op_sel_hi:[1,0]
	v_cvt_pk_bf16_f32 v32, v34, v35
	v_cvt_pk_bf16_f32 v33, v36, v37
	v_cvt_pk_bf16_f32 v34, v38, v39
	v_cvt_pk_bf16_f32 v35, v40, v41
	v_cvt_pk_bf16_f32 v36, v42, v43
	v_cvt_pk_bf16_f32 v37, v44, v45
	v_cvt_pk_bf16_f32 v38, v46, v47
	v_cvt_pk_bf16_f32 v39, v48, v49
	global_store_dwordx4 v[50:51], v[32:35], off
	global_store_dwordx4 v[50:51], v[36:39], off offset:256
	s_nop 1
	v_max_f32_e32 v32, v20, v20
	v_max_f32_e32 v37, v16, v16
	v_max_f32_e32 v39, v19, v19
	v_max_f32_e32 v19, 0, v29
	v_max_f32_e32 v29, 0, v23
	v_add_u32_e32 v16, 0xa0, v140
	v_max_f32_e32 v20, 0, v30
	v_max_f32_e32 v30, 0, v37
	v_max_f32_e32 v33, v21, v21
	v_max_f32_e32 v35, v22, v22
	v_max_f32_e32 v21, 0, v31
	v_max_f32_e32 v22, 0, v24
	v_max_f32_e32 v24, 0, v26
	v_max_f32_e32 v26, 0, v32
	v_max_f32_e32 v31, 0, v17
	v_max_f32_e32 v32, 0, v18
	v_ashrrev_i32_e32 v17, 31, v16
	v_lshlrev_b64 v[16:17], 13, v[16:17]
	v_lshl_add_u64 v[16:17], s[10:11], 0, v[16:17]
	v_lshl_add_u64 v[16:17], v[16:17], 0, s[26:27]
	v_max_f32_e32 v18, 0, v28
	v_max_f32_e32 v28, 0, v35
	v_max_f32_e32 v23, 0, v25
	v_max_f32_e32 v25, 0, v27
	v_max_f32_e32 v27, 0, v33
	v_max_f32_e32 v33, 0, v39
	v_pk_mul_f32 v[18:19], v[18:19], v[18:19]
	v_pk_mul_f32 v[20:21], v[20:21], v[20:21]
	v_pk_mul_f32 v[22:23], v[22:23], v[22:23]
	v_pk_mul_f32 v[24:25], v[24:25], v[24:25]
	v_pk_mul_f32 v[26:27], v[26:27], v[26:27]
	v_pk_mul_f32 v[28:29], v[28:29], v[28:29]
	v_pk_mul_f32 v[30:31], v[30:31], v[30:31]
	v_pk_mul_f32 v[32:33], v[32:33], v[32:33]
	s_waitcnt vmcnt(13)
	v_fmamk_f32 v36, v166, 0x3a800000, v205
	v_lshl_add_u64 v[34:35], v[16:17], 0, v[184:185]
	v_rcp_f32_e32 v16, v36
	s_nop 0
	v_pk_mul_f32 v[20:21], v[20:21], v[16:17] op_sel_hi:[1,0]
	v_pk_mul_f32 v[18:19], v[18:19], v[16:17] op_sel_hi:[1,0]
	v_pk_mul_f32 v[24:25], v[24:25], v[16:17] op_sel_hi:[1,0]
	v_pk_mul_f32 v[22:23], v[22:23], v[16:17] op_sel_hi:[1,0]
	v_pk_mul_f32 v[28:29], v[28:29], v[16:17] op_sel_hi:[1,0]
	v_pk_mul_f32 v[26:27], v[26:27], v[16:17] op_sel_hi:[1,0]
	v_pk_mul_f32 v[32:33], v[32:33], v[16:17] op_sel_hi:[1,0]
	v_pk_mul_f32 v[30:31], v[30:31], v[16:17] op_sel_hi:[1,0]
	v_cvt_pk_bf16_f32 v16, v18, v19
	v_cvt_pk_bf16_f32 v17, v20, v21
	v_cvt_pk_bf16_f32 v18, v22, v23
	v_cvt_pk_bf16_f32 v19, v24, v25
	v_cvt_pk_bf16_f32 v20, v26, v27
	v_cvt_pk_bf16_f32 v21, v28, v29
	v_cvt_pk_bf16_f32 v22, v30, v31
	v_cvt_pk_bf16_f32 v23, v32, v33
	global_store_dwordx4 v[34:35], v[16:19], off
	global_store_dwordx4 v[34:35], v[20:23], off offset:256
	s_nop 1
	v_max_f32_e32 v17, v5, v5
	v_max_f32_e32 v21, v0, v0
	v_add_u32_e32 v0, 0xb0, v140
	v_max_f32_e32 v5, 0, v15
	v_max_f32_e32 v15, 0, v1
	v_ashrrev_i32_e32 v1, 31, v0
	v_lshlrev_b64 v[0:1], 13, v[0:1]
	v_max_f32_e32 v23, v3, v3
	v_max_f32_e32 v3, 0, v13
	v_max_f32_e32 v13, 0, v7
	v_lshl_add_u64 v[0:1], s[10:11], 0, v[0:1]
	v_max_f32_e32 v16, v4, v4
	v_max_f32_e32 v4, 0, v14
	v_max_f32_e32 v14, 0, v21
	v_lshl_add_u64 v[0:1], v[0:1], 0, s[26:27]
	v_max_f32_e32 v19, v6, v6
	v_max_f32_e32 v6, 0, v8
	v_max_f32_e32 v8, 0, v10
	v_max_f32_e32 v10, 0, v16
	v_max_f32_e32 v16, 0, v2
	v_max_f32_e32 v2, 0, v12
	v_max_f32_e32 v12, 0, v19
	v_max_f32_e32 v7, 0, v9
	v_max_f32_e32 v9, 0, v11
	v_max_f32_e32 v11, 0, v17
	v_max_f32_e32 v17, 0, v23
	v_pk_mul_f32 v[2:3], v[2:3], v[2:3]
	v_pk_mul_f32 v[4:5], v[4:5], v[4:5]
	v_pk_mul_f32 v[6:7], v[6:7], v[6:7]
	v_pk_mul_f32 v[8:9], v[8:9], v[8:9]
	v_pk_mul_f32 v[10:11], v[10:11], v[10:11]
	v_pk_mul_f32 v[12:13], v[12:13], v[12:13]
	v_pk_mul_f32 v[14:15], v[14:15], v[14:15]
	v_pk_mul_f32 v[16:17], v[16:17], v[16:17]
	s_waitcnt vmcnt(14)
	v_fmamk_f32 v20, v167, 0x3a800000, v205
	v_lshl_add_u64 v[18:19], v[0:1], 0, v[184:185]
	v_rcp_f32_e32 v0, v20
	s_nop 0
	v_pk_mul_f32 v[4:5], v[4:5], v[0:1] op_sel_hi:[1,0]
	v_pk_mul_f32 v[2:3], v[2:3], v[0:1] op_sel_hi:[1,0]
	v_pk_mul_f32 v[8:9], v[8:9], v[0:1] op_sel_hi:[1,0]
	v_pk_mul_f32 v[6:7], v[6:7], v[0:1] op_sel_hi:[1,0]
	v_pk_mul_f32 v[12:13], v[12:13], v[0:1] op_sel_hi:[1,0]
	v_pk_mul_f32 v[10:11], v[10:11], v[0:1] op_sel_hi:[1,0]
	v_pk_mul_f32 v[16:17], v[16:17], v[0:1] op_sel_hi:[1,0]
	v_pk_mul_f32 v[14:15], v[14:15], v[0:1] op_sel_hi:[1,0]
	v_cvt_pk_bf16_f32 v0, v2, v3
	v_cvt_pk_bf16_f32 v1, v4, v5
	v_cvt_pk_bf16_f32 v2, v6, v7
	v_cvt_pk_bf16_f32 v3, v8, v9
	v_cvt_pk_bf16_f32 v4, v10, v11
	v_cvt_pk_bf16_f32 v5, v12, v13
	v_cvt_pk_bf16_f32 v6, v14, v15
	v_cvt_pk_bf16_f32 v7, v16, v17
	global_store_dwordx4 v[18:19], v[0:3], off
	global_store_dwordx4 v[18:19], v[4:7], off offset:256
	s_and_b64 vcc, exec, s[0:1]
	s_mov_b64 s[0:1], -1
	s_cbranch_vccnz .LBB0_320
	s_andn2_b64 vcc, exec, s[16:17]
	s_cbranch_vccnz .LBB0_319
	s_barrier
	s_branch .LBB0_319

; __device__ __forceinline__ unsigned pk2(float lo, float hi) { f32x2 v = {lo, hi}; bf16x2_hw b = __builtin_convertvector(v, bf16x2_hw); return __builtin_bit_cast(unsigned, b); }
; __device__ __forceinline__ void diffmix_block(const Grp& G, int b, int h, int qb, float lam, const float* subln, int tid) {
;     const int lane = tid & 63, wid = tid >> 6;
;     const float g0 = subln[2 * lane] * 0.8f, g1 = subln[2 * lane + 1] * 0.8f;
;     const size_t row0 = (size_t)b * TS + qb * 256 + wid * 32;
; #pragma unroll 1
;     for (int rb = 0; rb < 32; rb += 16) {
;         unsigned a[16], c[16];
; #pragma unroll
;         for (int r = 0; r < 16; ++r) { a[r] = *((const unsigned*)(G.DO + (row0 + rb + r) * 1024 + h * 128) + lane); c[r] = *((const unsigned*)(G.XN + (row0 + rb + r) * 1024 + h * 128) + lane); }
; #pragma unroll
;         for (int r = 0; r < 16; ++r) {
;             const float v0 = bflo(a[r]) - lam * bflo(c[r]), v1 = bfhi(a[r]) - lam * bfhi(c[r]);
;             const float ss = wave_sum(v0 * v0 + v1 * v1);
;             const float rs = 1.0f / sqrtf(ss * (1.f / 128.f) + EPSN);
;             *((unsigned*)(G.DO + (row0 + rb + r) * 1024 + h * 128) + lane) = pk2(v0 * rs * g0, v1 * rs * g1);
;         }
;     }
.LBB0_555:
	v_or_b32_e32 v11, s1, v9
	v_or_b32_e32 v10, s0, v8
	v_lshlrev_b64 v[50:51], 11, v[10:11]
	v_lshl_add_u64 v[52:53], v[2:3], 0, v[50:51]
	v_lshl_add_u64 v[10:11], v[4:5], 0, v[50:51]
	global_load_dword v59, v[52:53], off
	global_load_dword v60, v[10:11], off
	v_or_b32_e32 v10, 0x800, v50
	v_mov_b32_e32 v11, v51
	v_lshl_add_u64 v[54:55], v[2:3], 0, v[10:11]
	v_lshl_add_u64 v[10:11], v[4:5], 0, v[10:11]
	global_load_dword v61, v[54:55], off
	global_load_dword v62, v[10:11], off
	v_or_b32_e32 v10, 0x1000, v50
	v_mov_b32_e32 v11, v51
	v_lshl_add_u64 v[56:57], v[2:3], 0, v[10:11]
	v_lshl_add_u64 v[10:11], v[4:5], 0, v[10:11]
	global_load_dword v63, v[56:57], off
	global_load_dword v64, v[10:11], off
	v_or_b32_e32 v10, 0x1800, v50
	v_mov_b32_e32 v11, v51
	v_lshl_add_u64 v[34:35], v[2:3], 0, v[10:11]
	v_lshl_add_u64 v[10:11], v[4:5], 0, v[10:11]
	global_load_dword v65, v[34:35], off
	global_load_dword v66, v[10:11], off
	v_or_b32_e32 v10, 0x2000, v50
	v_mov_b32_e32 v11, v51
	v_lshl_add_u64 v[32:33], v[2:3], 0, v[10:11]
	v_lshl_add_u64 v[10:11], v[4:5], 0, v[10:11]
	global_load_dword v67, v[32:33], off
	global_load_dword v68, v[10:11], off
	v_or_b32_e32 v10, 0x2800, v50
	v_mov_b32_e32 v11, v51
	v_lshl_add_u64 v[30:31], v[2:3], 0, v[10:11]
	v_lshl_add_u64 v[10:11], v[4:5], 0, v[10:11]
	global_load_dword v69, v[30:31], off
	global_load_dword v70, v[10:11], off
	v_or_b32_e32 v10, 0x3000, v50
	v_mov_b32_e32 v11, v51
	v_lshl_add_u64 v[28:29], v[2:3], 0, v[10:11]
	v_lshl_add_u64 v[10:11], v[4:5], 0, v[10:11]
	global_load_dword v71, v[28:29], off
	global_load_dword v72, v[10:11], off
	v_or_b32_e32 v10, 0x3800, v50
	v_mov_b32_e32 v11, v51
	v_lshl_add_u64 v[26:27], v[2:3], 0, v[10:11]
	v_lshl_add_u64 v[10:11], v[4:5], 0, v[10:11]
	global_load_dword v73, v[26:27], off
	global_load_dword v74, v[10:11], off
	v_or_b32_e32 v10, 0x4000, v50
	v_mov_b32_e32 v11, v51
	v_lshl_add_u64 v[24:25], v[2:3], 0, v[10:11]
	v_lshl_add_u64 v[10:11], v[4:5], 0, v[10:11]
	global_load_dword v75, v[24:25], off
	global_load_dword v76, v[10:11], off
	v_or_b32_e32 v10, 0x4800, v50
	v_mov_b32_e32 v11, v51
	v_lshl_add_u64 v[22:23], v[2:3], 0, v[10:11]
	v_lshl_add_u64 v[10:11], v[4:5], 0, v[10:11]
	global_load_dword v48, v[22:23], off
	global_load_dword v49, v[10:11], off
	v_or_b32_e32 v10, 0x5000, v50
	v_mov_b32_e32 v11, v51
	v_lshl_add_u64 v[20:21], v[2:3], 0, v[10:11]
	v_lshl_add_u64 v[10:11], v[4:5], 0, v[10:11]
	global_load_dword v46, v[20:21], off
	global_load_dword v47, v[10:11], off
	v_or_b32_e32 v10, 0x5800, v50
	v_mov_b32_e32 v11, v51
	v_lshl_add_u64 v[18:19], v[2:3], 0, v[10:11]
	v_lshl_add_u64 v[10:11], v[4:5], 0, v[10:11]
	global_load_dword v44, v[18:19], off
	global_load_dword v45, v[10:11], off
	v_or_b32_e32 v10, 0x6000, v50
	v_mov_b32_e32 v11, v51
	v_lshl_add_u64 v[16:17], v[2:3], 0, v[10:11]
	v_lshl_add_u64 v[10:11], v[4:5], 0, v[10:11]
	global_load_dword v42, v[16:17], off
	global_load_dword v43, v[10:11], off
	v_or_b32_e32 v10, 0x6800, v50
	v_mov_b32_e32 v11, v51
	v_lshl_add_u64 v[14:15], v[2:3], 0, v[10:11]
	v_lshl_add_u64 v[10:11], v[4:5], 0, v[10:11]
	global_load_dword v40, v[14:15], off
	global_load_dword v41, v[10:11], off
	v_or_b32_e32 v10, 0x7000, v50
	v_mov_b32_e32 v11, v51
	v_lshl_add_u64 v[12:13], v[2:3], 0, v[10:11]
	v_lshl_add_u64 v[10:11], v[4:5], 0, v[10:11]
	v_or_b32_e32 v50, 0x7800, v50
	global_load_dword v38, v[12:13], off
	global_load_dword v39, v[10:11], off
	v_lshl_add_u64 v[10:11], v[2:3], 0, v[50:51]
	v_lshl_add_u64 v[50:51], v[4:5], 0, v[50:51]
	global_load_dword v36, v[10:11], off
	global_load_dword v37, v[50:51], off
	s_waitcnt vmcnt(0)
	v_lshlrev_b32_e32 v80, 16, v59
	v_lshlrev_b32_e32 v82, 16, v61
	v_lshlrev_b32_e32 v84, 16, v63
	v_lshlrev_b32_e32 v86, 16, v65
	v_lshlrev_b32_e32 v88, 16, v67
	v_lshlrev_b32_e32 v90, 16, v69
	v_lshlrev_b32_e32 v92, 16, v71
	v_lshlrev_b32_e32 v94, 16, v73
	v_lshlrev_b32_e32 v96, 16, v75
	v_lshlrev_b32_e32 v98, 16, v48
	v_lshlrev_b32_e32 v100, 16, v46
	v_lshlrev_b32_e32 v102, 16, v44
	v_lshlrev_b32_e32 v104, 16, v42
	v_lshlrev_b32_e32 v106, 16, v40
	v_lshlrev_b32_e32 v108, 16, v38
	v_lshlrev_b32_e32 v110, 16, v36
	v_lshlrev_b32_e32 v144, 16, v60
	v_lshlrev_b32_e32 v146, 16, v62
	v_lshlrev_b32_e32 v148, 16, v64
	v_lshlrev_b32_e32 v150, 16, v66
	v_lshlrev_b32_e32 v156, 16, v68
	v_lshlrev_b32_e32 v158, 16, v70
	v_lshlrev_b32_e32 v160, 16, v72
	v_lshlrev_b32_e32 v162, 16, v74
	v_lshlrev_b32_e32 v164, 16, v76
	v_lshlrev_b32_e32 v166, 16, v49
	v_lshlrev_b32_e32 v168, 16, v47
	v_lshlrev_b32_e32 v170, 16, v45
	v_lshlrev_b32_e32 v172, 16, v43
	v_lshlrev_b32_e32 v174, 16, v41
	v_lshlrev_b32_e32 v176, 16, v39
	v_lshlrev_b32_e32 v178, 16, v37
	v_and_b32_e32 v81, 0xffff0000, v59
	v_and_b32_e32 v83, 0xffff0000, v61
	v_and_b32_e32 v85, 0xffff0000, v63
	v_and_b32_e32 v87, 0xffff0000, v65
	v_and_b32_e32 v89, 0xffff0000, v67
	v_and_b32_e32 v91, 0xffff0000, v69
	v_and_b32_e32 v93, 0xffff0000, v71
	v_and_b32_e32 v95, 0xffff0000, v73
	v_and_b32_e32 v97, 0xffff0000, v75
	v_and_b32_e32 v99, 0xffff0000, v48
	v_and_b32_e32 v101, 0xffff0000, v46
	v_and_b32_e32 v103, 0xffff0000, v44
	v_and_b32_e32 v105, 0xffff0000, v42
	v_and_b32_e32 v107, 0xffff0000, v40
	v_and_b32_e32 v109, 0xffff0000, v38
	v_and_b32_e32 v111, 0xffff0000, v36
	v_and_b32_e32 v145, 0xffff0000, v60
	v_and_b32_e32 v147, 0xffff0000, v62
	v_and_b32_e32 v149, 0xffff0000, v64
	v_and_b32_e32 v151, 0xffff0000, v66
	v_and_b32_e32 v157, 0xffff0000, v68
	v_and_b32_e32 v159, 0xffff0000, v70
	v_and_b32_e32 v161, 0xffff0000, v72
	v_and_b32_e32 v163, 0xffff0000, v74
	v_and_b32_e32 v165, 0xffff0000, v76
	v_and_b32_e32 v167, 0xffff0000, v49
	v_and_b32_e32 v169, 0xffff0000, v47
; __device__ __forceinline__ unsigned pk2(float lo, float hi) { f32x2 v = {lo, hi}; bf16x2_hw b = __builtin_convertvector(v, bf16x2_hw); return __builtin_bit_cast(unsigned, b); }
; __device__ __forceinline__ void diffmix_block(const Grp& G, int b, int h, int qb, float lam, const float* subln, int tid) {
;     const int lane = tid & 63, wid = tid >> 6;
;     const float g0 = subln[2 * lane] * 0.8f, g1 = subln[2 * lane + 1] * 0.8f;
;     const size_t row0 = (size_t)b * TS + qb * 256 + wid * 32;
; #pragma unroll 1
;     for (int rb = 0; rb < 32; rb += 16) {
;         unsigned a[16], c[16];
; #pragma unroll
;         for (int r = 0; r < 16; ++r) { a[r] = *((const unsigned*)(G.DO + (row0 + rb + r) * 1024 + h * 128) + lane); c[r] = *((const unsigned*)(G.XN + (row0 + rb + r) * 1024 + h * 128) + lane); }
; #pragma unroll
;         for (int r = 0; r < 16; ++r) {
;             const float v0 = bflo(a[r]) - lam * bflo(c[r]), v1 = bfhi(a[r]) - lam * bfhi(c[r]);
;             const float ss = wave_sum(v0 * v0 + v1 * v1);
;             const float rs = 1.0f / sqrtf(ss * (1.f / 128.f) + EPSN);
;             *((unsigned*)(G.DO + (row0 + rb + r) * 1024 + h * 128) + lane) = pk2(v0 * rs * g0, v1 * rs * g1);
;         }
;     }
	v_and_b32_e32 v171, 0xffff0000, v45
	v_and_b32_e32 v173, 0xffff0000, v43
	v_and_b32_e32 v175, 0xffff0000, v41
	v_and_b32_e32 v177, 0xffff0000, v39
	v_and_b32_e32 v179, 0xffff0000, v37
	v_pk_fma_f32 v[80:81], v[192:193], v[144:145], v[80:81] neg_lo:[1,0,0] neg_hi:[1,0,0]
	v_pk_fma_f32 v[82:83], v[192:193], v[146:147], v[82:83] neg_lo:[1,0,0] neg_hi:[1,0,0]
	v_pk_fma_f32 v[84:85], v[192:193], v[148:149], v[84:85] neg_lo:[1,0,0] neg_hi:[1,0,0]
	v_pk_fma_f32 v[86:87], v[192:193], v[150:151], v[86:87] neg_lo:[1,0,0] neg_hi:[1,0,0]
	v_pk_fma_f32 v[88:89], v[192:193], v[156:157], v[88:89] neg_lo:[1,0,0] neg_hi:[1,0,0]
	v_pk_fma_f32 v[90:91], v[192:193], v[158:159], v[90:91] neg_lo:[1,0,0] neg_hi:[1,0,0]
	v_pk_fma_f32 v[92:93], v[192:193], v[160:161], v[92:93] neg_lo:[1,0,0] neg_hi:[1,0,0]
	v_pk_fma_f32 v[94:95], v[192:193], v[162:163], v[94:95] neg_lo:[1,0,0] neg_hi:[1,0,0]
	v_pk_fma_f32 v[96:97], v[192:193], v[164:165], v[96:97] neg_lo:[1,0,0] neg_hi:[1,0,0]
	v_pk_fma_f32 v[98:99], v[192:193], v[166:167], v[98:99] neg_lo:[1,0,0] neg_hi:[1,0,0]
	v_pk_fma_f32 v[100:101], v[192:193], v[168:169], v[100:101] neg_lo:[1,0,0] neg_hi:[1,0,0]
	v_pk_fma_f32 v[102:103], v[192:193], v[170:171], v[102:103] neg_lo:[1,0,0] neg_hi:[1,0,0]
	v_pk_fma_f32 v[104:105], v[192:193], v[172:173], v[104:105] neg_lo:[1,0,0] neg_hi:[1,0,0]
	v_pk_fma_f32 v[106:107], v[192:193], v[174:175], v[106:107] neg_lo:[1,0,0] neg_hi:[1,0,0]
	v_pk_fma_f32 v[108:109], v[192:193], v[176:177], v[108:109] neg_lo:[1,0,0] neg_hi:[1,0,0]
	v_pk_fma_f32 v[110:111], v[192:193], v[178:179], v[110:111] neg_lo:[1,0,0] neg_hi:[1,0,0]
	v_pk_mul_f32 v[144:145], v[80:81], v[80:81]
	v_pk_mul_f32 v[146:147], v[82:83], v[82:83]
	v_pk_mul_f32 v[148:149], v[84:85], v[84:85]
	v_pk_mul_f32 v[150:151], v[86:87], v[86:87]
	v_pk_mul_f32 v[156:157], v[88:89], v[88:89]
	v_pk_mul_f32 v[158:159], v[90:91], v[90:91]
	v_pk_mul_f32 v[160:161], v[92:93], v[92:93]
	v_pk_mul_f32 v[162:163], v[94:95], v[94:95]
	v_pk_mul_f32 v[164:165], v[96:97], v[96:97]
	v_pk_mul_f32 v[166:167], v[98:99], v[98:99]
	v_pk_mul_f32 v[168:169], v[100:101], v[100:101]
	v_pk_mul_f32 v[170:171], v[102:103], v[102:103]
	v_pk_mul_f32 v[172:173], v[104:105], v[104:105]
	v_pk_mul_f32 v[174:175], v[106:107], v[106:107]
	v_pk_mul_f32 v[176:177], v[108:109], v[108:109]
	v_pk_mul_f32 v[178:179], v[110:111], v[110:111]
	v_add_f32_e32 v112, v144, v145
	v_add_f32_e32 v114, v146, v147
	v_add_f32_e32 v116, v148, v149
	v_add_f32_e32 v118, v150, v151
	v_add_f32_e32 v120, v156, v157
	v_add_f32_e32 v122, v158, v159
	v_add_f32_e32 v124, v160, v161
	v_add_f32_e32 v126, v162, v163
	v_add_f32_e32 v128, v164, v165
	v_add_f32_e32 v130, v166, v167
	v_add_f32_e32 v132, v168, v169
	v_add_f32_e32 v134, v170, v171
	v_add_f32_e32 v136, v172, v173
	v_add_f32_e32 v138, v174, v175
	v_add_f32_e32 v140, v176, v177
	v_add_f32_e32 v142, v178, v179
	v_add_f32_dpp v112, v112, v112 quad_perm:[1,0,3,2] row_mask:0xf bank_mask:0xf
	v_add_f32_dpp v114, v114, v114 quad_perm:[1,0,3,2] row_mask:0xf bank_mask:0xf
	v_add_f32_dpp v116, v116, v116 quad_perm:[1,0,3,2] row_mask:0xf bank_mask:0xf
	v_add_f32_dpp v118, v118, v118 quad_perm:[1,0,3,2] row_mask:0xf bank_mask:0xf
	v_add_f32_dpp v120, v120, v120 quad_perm:[1,0,3,2] row_mask:0xf bank_mask:0xf
	v_add_f32_dpp v122, v122, v122 quad_perm:[1,0,3,2] row_mask:0xf bank_mask:0xf
	v_add_f32_dpp v124, v124, v124 quad_perm:[1,0,3,2] row_mask:0xf bank_mask:0xf
	v_add_f32_dpp v126, v126, v126 quad_perm:[1,0,3,2] row_mask:0xf bank_mask:0xf
	v_add_f32_dpp v128, v128, v128 quad_perm:[1,0,3,2] row_mask:0xf bank_mask:0xf
	v_add_f32_dpp v130, v130, v130 quad_perm:[1,0,3,2] row_mask:0xf bank_mask:0xf
	v_add_f32_dpp v132, v132, v132 quad_perm:[1,0,3,2] row_mask:0xf bank_mask:0xf
	v_add_f32_dpp v134, v134, v134 quad_perm:[1,0,3,2] row_mask:0xf bank_mask:0xf
	v_add_f32_dpp v136, v136, v136 quad_perm:[1,0,3,2] row_mask:0xf bank_mask:0xf
	v_add_f32_dpp v138, v138, v138 quad_perm:[1,0,3,2] row_mask:0xf bank_mask:0xf
	v_add_f32_dpp v140, v140, v140 quad_perm:[1,0,3,2] row_mask:0xf bank_mask:0xf
	v_add_f32_dpp v142, v142, v142 quad_perm:[1,0,3,2] row_mask:0xf bank_mask:0xf
	v_add_f32_dpp v112, v112, v112 quad_perm:[2,3,0,1] row_mask:0xf bank_mask:0xf
	v_add_f32_dpp v114, v114, v114 quad_perm:[2,3,0,1] row_mask:0xf bank_mask:0xf
	v_add_f32_dpp v116, v116, v116 quad_perm:[2,3,0,1] row_mask:0xf bank_mask:0xf
	v_add_f32_dpp v118, v118, v118 quad_perm:[2,3,0,1] row_mask:0xf bank_mask:0xf
	v_add_f32_dpp v120, v120, v120 quad_perm:[2,3,0,1] row_mask:0xf bank_mask:0xf
	v_add_f32_dpp v122, v122, v122 quad_perm:[2,3,0,1] row_mask:0xf bank_mask:0xf
	v_add_f32_dpp v124, v124, v124 quad_perm:[2,3,0,1] row_mask:0xf bank_mask:0xf
	v_add_f32_dpp v126, v126, v126 quad_perm:[2,3,0,1] row_mask:0xf bank_mask:0xf
	v_add_f32_dpp v128, v128, v128 quad_perm:[2,3,0,1] row_mask:0xf bank_mask:0xf
	v_add_f32_dpp v130, v130, v130 quad_perm:[2,3,0,1] row_mask:0xf bank_mask:0xf
	v_add_f32_dpp v132, v132, v132 quad_perm:[2,3,0,1] row_mask:0xf bank_mask:0xf
	v_add_f32_dpp v134, v134, v134 quad_perm:[2,3,0,1] row_mask:0xf bank_mask:0xf
	v_add_f32_dpp v136, v136, v136 quad_perm:[2,3,0,1] row_mask:0xf bank_mask:0xf
	v_add_f32_dpp v138, v138, v138 quad_perm:[2,3,0,1] row_mask:0xf bank_mask:0xf
	v_add_f32_dpp v140, v140, v140 quad_perm:[2,3,0,1] row_mask:0xf bank_mask:0xf
	v_add_f32_dpp v142, v142, v142 quad_perm:[2,3,0,1] row_mask:0xf bank_mask:0xf
	v_add_f32_dpp v112, v112, v112 row_half_mirror row_mask:0xf bank_mask:0xf
	v_add_f32_dpp v114, v114, v114 row_half_mirror row_mask:0xf bank_mask:0xf
	v_add_f32_dpp v116, v116, v116 row_half_mirror row_mask:0xf bank_mask:0xf
; __device__ __forceinline__ float half_sum32(float v) { v += swz_xor<1>(v); v += swz_xor<2>(v); v += swz_xor<4>(v); v += swz_xor<8>(v); v += swz_xor<16>(v); return v; }
; __device__ __forceinline__ unsigned pk2(float lo, float hi) { f32x2 v = {lo, hi}; bf16x2_hw b = __builtin_convertvector(v, bf16x2_hw); return __builtin_bit_cast(unsigned, b); }
; __device__ __forceinline__ float wave_sum(float v) {
;     v = half_sum32(v);
;     auto rr = __builtin_amdgcn_permlane32_swap(__float_as_uint(v), __float_as_uint(v), false, false);
;     return __uint_as_float(rr[0]) + __uint_as_float(rr[1]);
; __device__ __forceinline__ void diffmix_block(const Grp& G, int b, int h, int qb, float lam, const float* subln, int tid) {
;     const int lane = tid & 63, wid = tid >> 6;
;     const float g0 = subln[2 * lane] * 0.8f, g1 = subln[2 * lane + 1] * 0.8f;
;     const size_t row0 = (size_t)b * TS + qb * 256 + wid * 32;
; #pragma unroll 1
;     for (int rb = 0; rb < 32; rb += 16) {
;         unsigned a[16], c[16];
; #pragma unroll
;         for (int r = 0; r < 16; ++r) { a[r] = *((const unsigned*)(G.DO + (row0 + rb + r) * 1024 + h * 128) + lane); c[r] = *((const unsigned*)(G.XN + (row0 + rb + r) * 1024 + h * 128) + lane); }
; #pragma unroll
;         for (int r = 0; r < 16; ++r) {
;             const float v0 = bflo(a[r]) - lam * bflo(c[r]), v1 = bfhi(a[r]) - lam * bfhi(c[r]);
;             const float ss = wave_sum(v0 * v0 + v1 * v1);
;             const float rs = 1.0f / sqrtf(ss * (1.f / 128.f) + EPSN);
;             *((unsigned*)(G.DO + (row0 + rb + r) * 1024 + h * 128) + lane) = pk2(v0 * rs * g0, v1 * rs * g1);
;         }
;     }
	v_add_f32_dpp v118, v118, v118 row_half_mirror row_mask:0xf bank_mask:0xf
	v_add_f32_dpp v120, v120, v120 row_half_mirror row_mask:0xf bank_mask:0xf
	v_add_f32_dpp v122, v122, v122 row_half_mirror row_mask:0xf bank_mask:0xf
	v_add_f32_dpp v124, v124, v124 row_half_mirror row_mask:0xf bank_mask:0xf
	v_add_f32_dpp v126, v126, v126 row_half_mirror row_mask:0xf bank_mask:0xf
	v_add_f32_dpp v128, v128, v128 row_half_mirror row_mask:0xf bank_mask:0xf
	v_add_f32_dpp v130, v130, v130 row_half_mirror row_mask:0xf bank_mask:0xf
	v_add_f32_dpp v132, v132, v132 row_half_mirror row_mask:0xf bank_mask:0xf
	v_add_f32_dpp v134, v134, v134 row_half_mirror row_mask:0xf bank_mask:0xf
	v_add_f32_dpp v136, v136, v136 row_half_mirror row_mask:0xf bank_mask:0xf
	v_add_f32_dpp v138, v138, v138 row_half_mirror row_mask:0xf bank_mask:0xf
	v_add_f32_dpp v140, v140, v140 row_half_mirror row_mask:0xf bank_mask:0xf
	v_add_f32_dpp v142, v142, v142 row_half_mirror row_mask:0xf bank_mask:0xf
	v_add_f32_dpp v112, v112, v112 row_mirror row_mask:0xf bank_mask:0xf
	v_add_f32_dpp v114, v114, v114 row_mirror row_mask:0xf bank_mask:0xf
	v_add_f32_dpp v116, v116, v116 row_mirror row_mask:0xf bank_mask:0xf
	v_add_f32_dpp v118, v118, v118 row_mirror row_mask:0xf bank_mask:0xf
	v_add_f32_dpp v120, v120, v120 row_mirror row_mask:0xf bank_mask:0xf
	v_add_f32_dpp v122, v122, v122 row_mirror row_mask:0xf bank_mask:0xf
	v_add_f32_dpp v124, v124, v124 row_mirror row_mask:0xf bank_mask:0xf
	v_add_f32_dpp v126, v126, v126 row_mirror row_mask:0xf bank_mask:0xf
	v_add_f32_dpp v128, v128, v128 row_mirror row_mask:0xf bank_mask:0xf
	v_add_f32_dpp v130, v130, v130 row_mirror row_mask:0xf bank_mask:0xf
	v_add_f32_dpp v132, v132, v132 row_mirror row_mask:0xf bank_mask:0xf
	v_add_f32_dpp v134, v134, v134 row_mirror row_mask:0xf bank_mask:0xf
	v_add_f32_dpp v136, v136, v136 row_mirror row_mask:0xf bank_mask:0xf
	v_add_f32_dpp v138, v138, v138 row_mirror row_mask:0xf bank_mask:0xf
	v_add_f32_dpp v140, v140, v140 row_mirror row_mask:0xf bank_mask:0xf
	v_add_f32_dpp v142, v142, v142 row_mirror row_mask:0xf bank_mask:0xf
	v_mov_b32_e32 v144, v112
	v_mov_b32_e32 v146, v114
	v_mov_b32_e32 v148, v116
	v_mov_b32_e32 v150, v118
	v_mov_b32_e32 v156, v120
	v_mov_b32_e32 v158, v122
	v_mov_b32_e32 v160, v124
	v_mov_b32_e32 v162, v126
	v_mov_b32_e32 v164, v128
	v_mov_b32_e32 v166, v130
	v_mov_b32_e32 v168, v132
	v_mov_b32_e32 v170, v134
	v_mov_b32_e32 v172, v136
	v_mov_b32_e32 v174, v138
	v_mov_b32_e32 v176, v140
	v_mov_b32_e32 v178, v142
	v_permlane16_swap_b32_e32 v112, v144
	v_permlane16_swap_b32_e32 v114, v146
	v_permlane16_swap_b32_e32 v116, v148
	v_permlane16_swap_b32_e32 v118, v150
	v_permlane16_swap_b32_e32 v120, v156
	v_permlane16_swap_b32_e32 v122, v158
	v_permlane16_swap_b32_e32 v124, v160
	v_permlane16_swap_b32_e32 v126, v162
	v_permlane16_swap_b32_e32 v128, v164
	v_permlane16_swap_b32_e32 v130, v166
	v_permlane16_swap_b32_e32 v132, v168
	v_permlane16_swap_b32_e32 v134, v170
	v_permlane16_swap_b32_e32 v136, v172
	v_permlane16_swap_b32_e32 v138, v174
	v_permlane16_swap_b32_e32 v140, v176
	v_permlane16_swap_b32_e32 v142, v178
	v_add_f32_e32 v112, v112, v144
	v_add_f32_e32 v114, v114, v146
	v_add_f32_e32 v116, v116, v148
	v_add_f32_e32 v118, v118, v150
	v_add_f32_e32 v120, v120, v156
	v_add_f32_e32 v122, v122, v158
	v_add_f32_e32 v124, v124, v160
	v_add_f32_e32 v126, v126, v162
	v_add_f32_e32 v128, v128, v164
	v_add_f32_e32 v130, v130, v166
	v_add_f32_e32 v132, v132, v168
	v_add_f32_e32 v134, v134, v170
	v_add_f32_e32 v136, v136, v172
	v_add_f32_e32 v138, v138, v174
	v_add_f32_e32 v140, v140, v176
	v_add_f32_e32 v142, v142, v178
	v_mov_b32_e32 v144, v112
	v_mov_b32_e32 v146, v114
	v_mov_b32_e32 v148, v116
	v_mov_b32_e32 v150, v118
	v_mov_b32_e32 v156, v120
	v_mov_b32_e32 v158, v122
	v_mov_b32_e32 v160, v124
	v_mov_b32_e32 v162, v126
	v_mov_b32_e32 v164, v128
	v_mov_b32_e32 v166, v130
	v_mov_b32_e32 v168, v132
	v_mov_b32_e32 v170, v134
	v_mov_b32_e32 v172, v136
	v_mov_b32_e32 v174, v138
	v_mov_b32_e32 v176, v140
	v_mov_b32_e32 v178, v142
	v_permlane32_swap_b32_e32 v112, v144
	v_permlane32_swap_b32_e32 v114, v146
	v_permlane32_swap_b32_e32 v116, v148
	v_permlane32_swap_b32_e32 v118, v150
	v_permlane32_swap_b32_e32 v120, v156
	v_permlane32_swap_b32_e32 v122, v158
	v_permlane32_swap_b32_e32 v124, v160
	v_permlane32_swap_b32_e32 v126, v162
	v_permlane32_swap_b32_e32 v128, v164
	v_permlane32_swap_b32_e32 v130, v166
	v_permlane32_swap_b32_e32 v132, v168
	v_permlane32_swap_b32_e32 v134, v170
	v_permlane32_swap_b32_e32 v136, v172
	v_permlane32_swap_b32_e32 v138, v174
	v_permlane32_swap_b32_e32 v140, v176
	v_permlane32_swap_b32_e32 v142, v178
	v_add_f32_e32 v112, v112, v144
	v_add_f32_e32 v114, v114, v146
	v_add_f32_e32 v116, v116, v148
	v_add_f32_e32 v118, v118, v150
	v_add_f32_e32 v120, v120, v156
	v_add_f32_e32 v122, v122, v158
	v_add_f32_e32 v124, v124, v160
	v_add_f32_e32 v126, v126, v162
	v_add_f32_e32 v128, v128, v164
	v_add_f32_e32 v130, v130, v166
	v_add_f32_e32 v132, v132, v168
	v_add_f32_e32 v134, v134, v170
	v_add_f32_e32 v136, v136, v172
	v_add_f32_e32 v138, v138, v174
	v_add_f32_e32 v140, v140, v176
	v_add_f32_e32 v142, v142, v178
	v_fmamk_f32 v112, v112, 0x3c000000, v205
	v_cmp_gt_f32_e32 vcc, s63, v112
	v_mul_f32_e32 v180, 0x4f800000, v112
	s_nop 0
	v_cndmask_b32_e32 v112, v112, v180, vcc
	v_sqrt_f32_e32 v180, v112
	s_nop 0
	v_add_u32_e32 v181, -1, v180
	v_fma_f32 v182, -v181, v180, v112
	v_cmp_ge_f32_e64 s[0:1], 0, v182
	v_add_u32_e32 v182, 1, v180
	s_nop 0
	v_cndmask_b32_e64 v181, v180, v181, s[0:1]
	v_fma_f32 v180, -v182, v180, v112
	v_cmp_lt_f32_e64 s[0:1], 0, v180
	s_nop 1
; __device__ __forceinline__ unsigned pk2(float lo, float hi) { f32x2 v = {lo, hi}; bf16x2_hw b = __builtin_convertvector(v, bf16x2_hw); return __builtin_bit_cast(unsigned, b); }
; __device__ __forceinline__ void diffmix_block(const Grp& G, int b, int h, int qb, float lam, const float* subln, int tid) {
;     ...
;             const float ss = wave_sum(v0 * v0 + v1 * v1);
;             const float rs = 1.0f / sqrtf(ss * (1.f / 128.f) + EPSN);
;             *((unsigned*)(G.DO + (row0 + rb + r) * 1024 + h * 128) + lane) = pk2(v0 * rs * g0, v1 * rs * g1);
	v_cndmask_b32_e64 v180, v181, v182, s[0:1]
	v_mul_f32_e32 v181, 0x37800000, v180
	v_cndmask_b32_e32 v180, v180, v181, vcc
	v_cmp_class_f32_e32 vcc, v112, v206
	s_nop 1
	v_cndmask_b32_e32 v112, v180, v112, vcc
	v_rcp_f32_e32 v112, v112
	s_nop 0
	v_pk_mul_f32 v[80:81], v[80:81], v[112:113] op_sel_hi:[1,0]
	s_nop 0
	v_pk_mul_f32 v[80:81], v[0:1], v[80:81]
	s_nop 0
	v_cvt_pk_bf16_f32 v80, v80, v81
	global_store_dword v[52:53], v80, off
	v_fmamk_f32 v114, v114, 0x3c000000, v205
	v_cmp_gt_f32_e32 vcc, s63, v114
	v_mul_f32_e32 v180, 0x4f800000, v114
	s_nop 0
	v_cndmask_b32_e32 v114, v114, v180, vcc
	v_sqrt_f32_e32 v180, v114
	s_nop 0
	v_add_u32_e32 v181, -1, v180
	v_fma_f32 v182, -v181, v180, v114
	v_cmp_ge_f32_e64 s[0:1], 0, v182
	v_add_u32_e32 v182, 1, v180
	s_nop 0
	v_cndmask_b32_e64 v181, v180, v181, s[0:1]
	v_fma_f32 v180, -v182, v180, v114
	v_cmp_lt_f32_e64 s[0:1], 0, v180
	s_nop 1
	v_cndmask_b32_e64 v180, v181, v182, s[0:1]
	v_mul_f32_e32 v181, 0x37800000, v180
	v_cndmask_b32_e32 v180, v180, v181, vcc
	v_cmp_class_f32_e32 vcc, v114, v206
	s_nop 1
	v_cndmask_b32_e32 v114, v180, v114, vcc
	v_rcp_f32_e32 v114, v114
	s_nop 0
	v_pk_mul_f32 v[82:83], v[82:83], v[114:115] op_sel_hi:[1,0]
	s_nop 0
	v_pk_mul_f32 v[82:83], v[0:1], v[82:83]
	s_nop 0
	v_cvt_pk_bf16_f32 v82, v82, v83
	global_store_dword v[54:55], v82, off
	v_fmamk_f32 v116, v116, 0x3c000000, v205
	v_cmp_gt_f32_e32 vcc, s63, v116
	v_mul_f32_e32 v180, 0x4f800000, v116
	s_nop 0
	v_cndmask_b32_e32 v116, v116, v180, vcc
	v_sqrt_f32_e32 v180, v116
	s_nop 0
	v_add_u32_e32 v181, -1, v180
	v_fma_f32 v182, -v181, v180, v116
	v_cmp_ge_f32_e64 s[0:1], 0, v182
	v_add_u32_e32 v182, 1, v180
	s_nop 0
	v_cndmask_b32_e64 v181, v180, v181, s[0:1]
	v_fma_f32 v180, -v182, v180, v116
	v_cmp_lt_f32_e64 s[0:1], 0, v180
	s_nop 1
	v_cndmask_b32_e64 v180, v181, v182, s[0:1]
	v_mul_f32_e32 v181, 0x37800000, v180
	v_cndmask_b32_e32 v180, v180, v181, vcc
	v_cmp_class_f32_e32 vcc, v116, v206
	s_nop 1
	v_cndmask_b32_e32 v116, v180, v116, vcc
	v_rcp_f32_e32 v116, v116
	s_nop 0
	v_pk_mul_f32 v[84:85], v[84:85], v[116:117] op_sel_hi:[1,0]
	s_nop 0
	v_pk_mul_f32 v[84:85], v[0:1], v[84:85]
	s_nop 0
	v_cvt_pk_bf16_f32 v84, v84, v85
	global_store_dword v[56:57], v84, off
	v_fmamk_f32 v118, v118, 0x3c000000, v205
	v_cmp_gt_f32_e32 vcc, s63, v118
	v_mul_f32_e32 v180, 0x4f800000, v118
	s_nop 0
	v_cndmask_b32_e32 v118, v118, v180, vcc
	v_sqrt_f32_e32 v180, v118
	s_nop 0
	v_add_u32_e32 v181, -1, v180
	v_fma_f32 v182, -v181, v180, v118
	v_cmp_ge_f32_e64 s[0:1], 0, v182
	v_add_u32_e32 v182, 1, v180
	s_nop 0
	v_cndmask_b32_e64 v181, v180, v181, s[0:1]
	v_fma_f32 v180, -v182, v180, v118
	v_cmp_lt_f32_e64 s[0:1], 0, v180
	s_nop 1
	v_cndmask_b32_e64 v180, v181, v182, s[0:1]
	v_mul_f32_e32 v181, 0x37800000, v180
	v_cndmask_b32_e32 v180, v180, v181, vcc
	v_cmp_class_f32_e32 vcc, v118, v206
	s_nop 1
	v_cndmask_b32_e32 v118, v180, v118, vcc
	v_rcp_f32_e32 v118, v118
	s_nop 0
	v_pk_mul_f32 v[86:87], v[86:87], v[118:119] op_sel_hi:[1,0]
	s_nop 0
	v_pk_mul_f32 v[86:87], v[0:1], v[86:87]
	s_nop 0
	v_cvt_pk_bf16_f32 v86, v86, v87
	global_store_dword v[34:35], v86, off
	v_fmamk_f32 v120, v120, 0x3c000000, v205
	v_cmp_gt_f32_e32 vcc, s63, v120
	v_mul_f32_e32 v180, 0x4f800000, v120
	s_nop 0
	v_cndmask_b32_e32 v120, v120, v180, vcc
	v_sqrt_f32_e32 v180, v120
	s_nop 0
	v_add_u32_e32 v181, -1, v180
	v_fma_f32 v182, -v181, v180, v120
	v_cmp_ge_f32_e64 s[0:1], 0, v182
	v_add_u32_e32 v182, 1, v180
	s_nop 0
	v_cndmask_b32_e64 v181, v180, v181, s[0:1]
	v_fma_f32 v180, -v182, v180, v120
	v_cmp_lt_f32_e64 s[0:1], 0, v180
	s_nop 1
	v_cndmask_b32_e64 v180, v181, v182, s[0:1]
	v_mul_f32_e32 v181, 0x37800000, v180
	v_cndmask_b32_e32 v180, v180, v181, vcc
	v_cmp_class_f32_e32 vcc, v120, v206
	s_nop 1
	v_cndmask_b32_e32 v120, v180, v120, vcc
	v_rcp_f32_e32 v120, v120
	s_nop 0
	v_pk_mul_f32 v[88:89], v[88:89], v[120:121] op_sel_hi:[1,0]
	s_nop 0
	v_pk_mul_f32 v[88:89], v[0:1], v[88:89]
	s_nop 0
	v_cvt_pk_bf16_f32 v88, v88, v89
	global_store_dword v[32:33], v88, off
	v_fmamk_f32 v122, v122, 0x3c000000, v205
	v_cmp_gt_f32_e32 vcc, s63, v122
	v_mul_f32_e32 v180, 0x4f800000, v122
	s_nop 0
	v_cndmask_b32_e32 v122, v122, v180, vcc
	v_sqrt_f32_e32 v180, v122
	s_nop 0
	v_add_u32_e32 v181, -1, v180
	v_fma_f32 v182, -v181, v180, v122
	v_cmp_ge_f32_e64 s[0:1], 0, v182
	v_add_u32_e32 v182, 1, v180
	s_nop 0
	v_cndmask_b32_e64 v181, v180, v181, s[0:1]
	v_fma_f32 v180, -v182, v180, v122
	v_cmp_lt_f32_e64 s[0:1], 0, v180
	s_nop 1
	v_cndmask_b32_e64 v180, v181, v182, s[0:1]
	v_mul_f32_e32 v181, 0x37800000, v180
	v_cndmask_b32_e32 v180, v180, v181, vcc
	v_cmp_class_f32_e32 vcc, v122, v206
	s_nop 1
	v_cndmask_b32_e32 v122, v180, v122, vcc
	v_rcp_f32_e32 v122, v122
	s_nop 0
	v_pk_mul_f32 v[90:91], v[90:91], v[122:123] op_sel_hi:[1,0]
	s_nop 0
	v_pk_mul_f32 v[90:91], v[0:1], v[90:91]
	s_nop 0
	v_cvt_pk_bf16_f32 v90, v90, v91
	global_store_dword v[30:31], v90, off
	v_fmamk_f32 v124, v124, 0x3c000000, v205
	v_cmp_gt_f32_e32 vcc, s63, v124
	v_mul_f32_e32 v180, 0x4f800000, v124
	s_nop 0
	v_cndmask_b32_e32 v124, v124, v180, vcc
	v_sqrt_f32_e32 v180, v124
	s_nop 0
	v_add_u32_e32 v181, -1, v180
	v_fma_f32 v182, -v181, v180, v124
	v_cmp_ge_f32_e64 s[0:1], 0, v182
	v_add_u32_e32 v182, 1, v180
	s_nop 0
	v_cndmask_b32_e64 v181, v180, v181, s[0:1]
	v_fma_f32 v180, -v182, v180, v124
	v_cmp_lt_f32_e64 s[0:1], 0, v180
	s_nop 1
	v_cndmask_b32_e64 v180, v181, v182, s[0:1]
	v_mul_f32_e32 v181, 0x37800000, v180
	v_cndmask_b32_e32 v180, v180, v181, vcc
	v_cmp_class_f32_e32 vcc, v124, v206
	s_nop 1
	v_cndmask_b32_e32 v124, v180, v124, vcc
	v_rcp_f32_e32 v124, v124
	s_nop 0
; __device__ __forceinline__ unsigned pk2(float lo, float hi) { f32x2 v = {lo, hi}; bf16x2_hw b = __builtin_convertvector(v, bf16x2_hw); return __builtin_bit_cast(unsigned, b); }
; __device__ __forceinline__ void diffmix_block(const Grp& G, int b, int h, int qb, float lam, const float* subln, int tid) {
;     ...
;         for (int r = 0; r < 16; ++r) {
;             const float v0 = bflo(a[r]) - lam * bflo(c[r]), v1 = bfhi(a[r]) - lam * bfhi(c[r]);
;             const float ss = wave_sum(v0 * v0 + v1 * v1);
;             const float rs = 1.0f / sqrtf(ss * (1.f / 128.f) + EPSN);
;             *((unsigned*)(G.DO + (row0 + rb + r) * 1024 + h * 128) + lane) = pk2(v0 * rs * g0, v1 * rs * g1);
;         }
	v_pk_mul_f32 v[92:93], v[92:93], v[124:125] op_sel_hi:[1,0]
	s_nop 0
	v_pk_mul_f32 v[92:93], v[0:1], v[92:93]
	s_nop 0
	v_cvt_pk_bf16_f32 v92, v92, v93
	global_store_dword v[28:29], v92, off
	v_fmamk_f32 v126, v126, 0x3c000000, v205
	v_cmp_gt_f32_e32 vcc, s63, v126
	v_mul_f32_e32 v180, 0x4f800000, v126
	s_nop 0
	v_cndmask_b32_e32 v126, v126, v180, vcc
	v_sqrt_f32_e32 v180, v126
	s_nop 0
	v_add_u32_e32 v181, -1, v180
	v_fma_f32 v182, -v181, v180, v126
	v_cmp_ge_f32_e64 s[0:1], 0, v182
	v_add_u32_e32 v182, 1, v180
	s_nop 0
	v_cndmask_b32_e64 v181, v180, v181, s[0:1]
	v_fma_f32 v180, -v182, v180, v126
	v_cmp_lt_f32_e64 s[0:1], 0, v180
	s_nop 1
	v_cndmask_b32_e64 v180, v181, v182, s[0:1]
	v_mul_f32_e32 v181, 0x37800000, v180
	v_cndmask_b32_e32 v180, v180, v181, vcc
	v_cmp_class_f32_e32 vcc, v126, v206
	s_nop 1
	v_cndmask_b32_e32 v126, v180, v126, vcc
	v_rcp_f32_e32 v126, v126
	s_nop 0
	v_pk_mul_f32 v[94:95], v[94:95], v[126:127] op_sel_hi:[1,0]
	s_nop 0
	v_pk_mul_f32 v[94:95], v[0:1], v[94:95]
	s_nop 0
	v_cvt_pk_bf16_f32 v94, v94, v95
	global_store_dword v[26:27], v94, off
	v_fmamk_f32 v128, v128, 0x3c000000, v205
	v_cmp_gt_f32_e32 vcc, s63, v128
	v_mul_f32_e32 v180, 0x4f800000, v128
	s_nop 0
	v_cndmask_b32_e32 v128, v128, v180, vcc
	v_sqrt_f32_e32 v180, v128
	s_nop 0
	v_add_u32_e32 v181, -1, v180
	v_fma_f32 v182, -v181, v180, v128
	v_cmp_ge_f32_e64 s[0:1], 0, v182
	v_add_u32_e32 v182, 1, v180
	s_nop 0
	v_cndmask_b32_e64 v181, v180, v181, s[0:1]
	v_fma_f32 v180, -v182, v180, v128
	v_cmp_lt_f32_e64 s[0:1], 0, v180
	s_nop 1
	v_cndmask_b32_e64 v180, v181, v182, s[0:1]
	v_mul_f32_e32 v181, 0x37800000, v180
	v_cndmask_b32_e32 v180, v180, v181, vcc
	v_cmp_class_f32_e32 vcc, v128, v206
	s_nop 1
	v_cndmask_b32_e32 v128, v180, v128, vcc
	v_rcp_f32_e32 v128, v128
	s_nop 0
	v_pk_mul_f32 v[96:97], v[96:97], v[128:129] op_sel_hi:[1,0]
	s_nop 0
	v_pk_mul_f32 v[96:97], v[0:1], v[96:97]
	s_nop 0
	v_cvt_pk_bf16_f32 v96, v96, v97
	global_store_dword v[24:25], v96, off
	v_fmamk_f32 v130, v130, 0x3c000000, v205
	v_cmp_gt_f32_e32 vcc, s63, v130
	v_mul_f32_e32 v180, 0x4f800000, v130
	s_nop 0
	v_cndmask_b32_e32 v130, v130, v180, vcc
	v_sqrt_f32_e32 v180, v130
	s_nop 0
	v_add_u32_e32 v181, -1, v180
	v_fma_f32 v182, -v181, v180, v130
	v_cmp_ge_f32_e64 s[0:1], 0, v182
	v_add_u32_e32 v182, 1, v180
	s_nop 0
	v_cndmask_b32_e64 v181, v180, v181, s[0:1]
	v_fma_f32 v180, -v182, v180, v130
	v_cmp_lt_f32_e64 s[0:1], 0, v180
	s_nop 1
	v_cndmask_b32_e64 v180, v181, v182, s[0:1]
	v_mul_f32_e32 v181, 0x37800000, v180
	v_cndmask_b32_e32 v180, v180, v181, vcc
	v_cmp_class_f32_e32 vcc, v130, v206
	s_nop 1
	v_cndmask_b32_e32 v130, v180, v130, vcc
	v_rcp_f32_e32 v130, v130
	s_nop 0
	v_pk_mul_f32 v[98:99], v[98:99], v[130:131] op_sel_hi:[1,0]
	s_nop 0
	v_pk_mul_f32 v[98:99], v[0:1], v[98:99]
	s_nop 0
	v_cvt_pk_bf16_f32 v98, v98, v99
	global_store_dword v[22:23], v98, off
	v_fmamk_f32 v132, v132, 0x3c000000, v205
	v_cmp_gt_f32_e32 vcc, s63, v132
	v_mul_f32_e32 v180, 0x4f800000, v132
	s_nop 0
	v_cndmask_b32_e32 v132, v132, v180, vcc
	v_sqrt_f32_e32 v180, v132
	s_nop 0
	v_add_u32_e32 v181, -1, v180
	v_fma_f32 v182, -v181, v180, v132
	v_cmp_ge_f32_e64 s[0:1], 0, v182
	v_add_u32_e32 v182, 1, v180
	s_nop 0
	v_cndmask_b32_e64 v181, v180, v181, s[0:1]
	v_fma_f32 v180, -v182, v180, v132
	v_cmp_lt_f32_e64 s[0:1], 0, v180
	s_nop 1
	v_cndmask_b32_e64 v180, v181, v182, s[0:1]
	v_mul_f32_e32 v181, 0x37800000, v180
	v_cndmask_b32_e32 v180, v180, v181, vcc
	v_cmp_class_f32_e32 vcc, v132, v206
	s_nop 1
	v_cndmask_b32_e32 v132, v180, v132, vcc
	v_rcp_f32_e32 v132, v132
	s_nop 0
	v_pk_mul_f32 v[100:101], v[100:101], v[132:133] op_sel_hi:[1,0]
	s_nop 0
	v_pk_mul_f32 v[100:101], v[0:1], v[100:101]
	s_nop 0
	v_cvt_pk_bf16_f32 v100, v100, v101
	global_store_dword v[20:21], v100, off
	v_fmamk_f32 v134, v134, 0x3c000000, v205
	v_cmp_gt_f32_e32 vcc, s63, v134
	v_mul_f32_e32 v180, 0x4f800000, v134
	s_nop 0
	v_cndmask_b32_e32 v134, v134, v180, vcc
	v_sqrt_f32_e32 v180, v134
	s_nop 0
	v_add_u32_e32 v181, -1, v180
	v_fma_f32 v182, -v181, v180, v134
	v_cmp_ge_f32_e64 s[0:1], 0, v182
	v_add_u32_e32 v182, 1, v180
	s_nop 0
	v_cndmask_b32_e64 v181, v180, v181, s[0:1]
	v_fma_f32 v180, -v182, v180, v134
	v_cmp_lt_f32_e64 s[0:1], 0, v180
	s_nop 1
	v_cndmask_b32_e64 v180, v181, v182, s[0:1]
	v_mul_f32_e32 v181, 0x37800000, v180
	v_cndmask_b32_e32 v180, v180, v181, vcc
	v_cmp_class_f32_e32 vcc, v134, v206
	s_nop 1
	v_cndmask_b32_e32 v134, v180, v134, vcc
	v_rcp_f32_e32 v134, v134
	s_nop 0
	v_pk_mul_f32 v[102:103], v[102:103], v[134:135] op_sel_hi:[1,0]
	s_nop 0
	v_pk_mul_f32 v[102:103], v[0:1], v[102:103]
	s_nop 0
	v_cvt_pk_bf16_f32 v102, v102, v103
	global_store_dword v[18:19], v102, off
	v_fmamk_f32 v136, v136, 0x3c000000, v205
	v_cmp_gt_f32_e32 vcc, s63, v136
	v_mul_f32_e32 v180, 0x4f800000, v136
	s_nop 0
	v_cndmask_b32_e32 v136, v136, v180, vcc
	v_sqrt_f32_e32 v180, v136
	s_nop 0
	v_add_u32_e32 v181, -1, v180
	v_fma_f32 v182, -v181, v180, v136
	v_cmp_ge_f32_e64 s[0:1], 0, v182
	v_add_u32_e32 v182, 1, v180
	s_nop 0
	v_cndmask_b32_e64 v181, v180, v181, s[0:1]
	v_fma_f32 v180, -v182, v180, v136
	v_cmp_lt_f32_e64 s[0:1], 0, v180
	s_nop 1
	v_cndmask_b32_e64 v180, v181, v182, s[0:1]
	v_mul_f32_e32 v181, 0x37800000, v180
	v_cndmask_b32_e32 v180, v180, v181, vcc
	v_cmp_class_f32_e32 vcc, v136, v206
	s_nop 1
	v_cndmask_b32_e32 v136, v180, v136, vcc
	v_rcp_f32_e32 v136, v136
	s_nop 0
	v_pk_mul_f32 v[104:105], v[104:105], v[136:137] op_sel_hi:[1,0]
	s_nop 0
	v_pk_mul_f32 v[104:105], v[0:1], v[104:105]
	s_nop 0
	v_cvt_pk_bf16_f32 v104, v104, v105
	global_store_dword v[16:17], v104, off
	v_fmamk_f32 v138, v138, 0x3c000000, v205
; __device__ __forceinline__ unsigned pk2(float lo, float hi) { f32x2 v = {lo, hi}; bf16x2_hw b = __builtin_convertvector(v, bf16x2_hw); return __builtin_bit_cast(unsigned, b); }
; __device__ __forceinline__ void diffmix_block(const Grp& G, int b, int h, int qb, float lam, const float* subln, int tid) {
;     ...
;         for (int r = 0; r < 16; ++r) { a[r] = *((const unsigned*)(G.DO + (row0 + rb + r) * 1024 + h * 128) + lane); c[r] = *((const unsigned*)(G.XN + (row0 + rb + r) * 1024 + h * 128) + lane); }
; #pragma unroll
;         for (int r = 0; r < 16; ++r) {
;             const float v0 = bflo(a[r]) - lam * bflo(c[r]), v1 = bfhi(a[r]) - lam * bfhi(c[r]);
;             const float ss = wave_sum(v0 * v0 + v1 * v1);
;             const float rs = 1.0f / sqrtf(ss * (1.f / 128.f) + EPSN);
;             *((unsigned*)(G.DO + (row0 + rb + r) * 1024 + h * 128) + lane) = pk2(v0 * rs * g0, v1 * rs * g1);
;         }
	v_cmp_gt_f32_e32 vcc, s63, v138
	v_mul_f32_e32 v180, 0x4f800000, v138
	s_nop 0
	v_cndmask_b32_e32 v138, v138, v180, vcc
	v_sqrt_f32_e32 v180, v138
	s_nop 0
	v_add_u32_e32 v181, -1, v180
	v_fma_f32 v182, -v181, v180, v138
	v_cmp_ge_f32_e64 s[0:1], 0, v182
	v_add_u32_e32 v182, 1, v180
	s_nop 0
	v_cndmask_b32_e64 v181, v180, v181, s[0:1]
	v_fma_f32 v180, -v182, v180, v138
	v_cmp_lt_f32_e64 s[0:1], 0, v180
	s_nop 1
	v_cndmask_b32_e64 v180, v181, v182, s[0:1]
	v_mul_f32_e32 v181, 0x37800000, v180
	v_cndmask_b32_e32 v180, v180, v181, vcc
	v_cmp_class_f32_e32 vcc, v138, v206
	s_nop 1
	v_cndmask_b32_e32 v138, v180, v138, vcc
	v_rcp_f32_e32 v138, v138
	s_nop 0
	v_pk_mul_f32 v[106:107], v[106:107], v[138:139] op_sel_hi:[1,0]
	s_nop 0
	v_pk_mul_f32 v[106:107], v[0:1], v[106:107]
	s_nop 0
	v_cvt_pk_bf16_f32 v106, v106, v107
	global_store_dword v[14:15], v106, off
	v_fmamk_f32 v140, v140, 0x3c000000, v205
	v_cmp_gt_f32_e32 vcc, s63, v140
	v_mul_f32_e32 v180, 0x4f800000, v140
	s_nop 0
	v_cndmask_b32_e32 v140, v140, v180, vcc
	v_sqrt_f32_e32 v180, v140
	s_nop 0
	v_add_u32_e32 v181, -1, v180
	v_fma_f32 v182, -v181, v180, v140
	v_cmp_ge_f32_e64 s[0:1], 0, v182
	v_add_u32_e32 v182, 1, v180
	s_nop 0
	v_cndmask_b32_e64 v181, v180, v181, s[0:1]
	v_fma_f32 v180, -v182, v180, v140
	v_cmp_lt_f32_e64 s[0:1], 0, v180
	s_nop 1
	v_cndmask_b32_e64 v180, v181, v182, s[0:1]
	v_mul_f32_e32 v181, 0x37800000, v180
	v_cndmask_b32_e32 v180, v180, v181, vcc
	v_cmp_class_f32_e32 vcc, v140, v206
	s_nop 1
	v_cndmask_b32_e32 v140, v180, v140, vcc
	v_rcp_f32_e32 v140, v140
	s_nop 0
	v_pk_mul_f32 v[108:109], v[108:109], v[140:141] op_sel_hi:[1,0]
	s_nop 0
	v_pk_mul_f32 v[108:109], v[0:1], v[108:109]
	s_nop 0
	v_cvt_pk_bf16_f32 v108, v108, v109
	global_store_dword v[12:13], v108, off
	v_fmamk_f32 v142, v142, 0x3c000000, v205
	v_cmp_gt_f32_e32 vcc, s63, v142
	v_mul_f32_e32 v180, 0x4f800000, v142
	s_nop 0
	v_cndmask_b32_e32 v142, v142, v180, vcc
	v_sqrt_f32_e32 v180, v142
	s_nop 0
	v_add_u32_e32 v181, -1, v180
	v_fma_f32 v182, -v181, v180, v142
	v_cmp_ge_f32_e64 s[0:1], 0, v182
	v_add_u32_e32 v182, 1, v180
	s_nop 0
	v_cndmask_b32_e64 v181, v180, v181, s[0:1]
	v_fma_f32 v180, -v182, v180, v142
	v_cmp_lt_f32_e64 s[0:1], 0, v180
	s_nop 1
	v_cndmask_b32_e64 v180, v181, v182, s[0:1]
	v_mul_f32_e32 v181, 0x37800000, v180
	v_cndmask_b32_e32 v180, v180, v181, vcc
	v_cmp_class_f32_e32 vcc, v142, v206
	s_nop 1
	v_cndmask_b32_e32 v142, v180, v142, vcc
	v_rcp_f32_e32 v142, v142
	s_nop 0
	v_pk_mul_f32 v[110:111], v[110:111], v[142:143] op_sel_hi:[1,0]
	s_nop 0
	v_pk_mul_f32 v[110:111], v[0:1], v[110:111]
	s_nop 0
	v_cvt_pk_bf16_f32 v110, v110, v111
	global_store_dword v[10:11], v110, off
	s_mov_b64 s[0:1], 16
	s_and_b64 vcc, exec, s[2:3]
	s_mov_b64 s[2:3], 0
	s_cbranch_vccnz .LBB0_555
	s_or_b64 s[0:1], s[24:25], s[4:5]
	v_lshl_add_u64 v[6:7], s[0:1], 0, v[6:7]
	s_mov_b64 s[0:1], 0
	s_mov_b64 s[2:3], -1
.LBB0_557:
	v_or_b32_e32 v9, s1, v7
	v_or_b32_e32 v8, s0, v6
	v_lshlrev_b64 v[48:49], 11, v[8:9]
	v_lshl_add_u64 v[50:51], v[2:3], 0, v[48:49]
	v_lshl_add_u64 v[8:9], v[4:5], 0, v[48:49]
	global_load_dword v57, v[50:51], off
	global_load_dword v58, v[8:9], off
	v_or_b32_e32 v8, 0x800, v48
	v_mov_b32_e32 v9, v49
	v_lshl_add_u64 v[52:53], v[2:3], 0, v[8:9]
	v_lshl_add_u64 v[8:9], v[4:5], 0, v[8:9]
	global_load_dword v59, v[52:53], off
	global_load_dword v60, v[8:9], off
	v_or_b32_e32 v8, 0x1000, v48
	v_mov_b32_e32 v9, v49
	v_lshl_add_u64 v[54:55], v[2:3], 0, v[8:9]
	v_lshl_add_u64 v[8:9], v[4:5], 0, v[8:9]
	global_load_dword v61, v[54:55], off
	global_load_dword v62, v[8:9], off
	v_or_b32_e32 v8, 0x1800, v48
	v_mov_b32_e32 v9, v49
	v_lshl_add_u64 v[32:33], v[2:3], 0, v[8:9]
	v_lshl_add_u64 v[8:9], v[4:5], 0, v[8:9]
	global_load_dword v63, v[32:33], off
	global_load_dword v64, v[8:9], off
	v_or_b32_e32 v8, 0x2000, v48
	v_mov_b32_e32 v9, v49
	v_lshl_add_u64 v[30:31], v[2:3], 0, v[8:9]
	v_lshl_add_u64 v[8:9], v[4:5], 0, v[8:9]
	global_load_dword v65, v[30:31], off
	global_load_dword v66, v[8:9], off
	v_or_b32_e32 v8, 0x2800, v48
	v_mov_b32_e32 v9, v49
	v_lshl_add_u64 v[28:29], v[2:3], 0, v[8:9]
	v_lshl_add_u64 v[8:9], v[4:5], 0, v[8:9]
	global_load_dword v67, v[28:29], off
	global_load_dword v68, v[8:9], off
	v_or_b32_e32 v8, 0x3000, v48
	v_mov_b32_e32 v9, v49
	v_lshl_add_u64 v[26:27], v[2:3], 0, v[8:9]
	v_lshl_add_u64 v[8:9], v[4:5], 0, v[8:9]
	global_load_dword v69, v[26:27], off
	global_load_dword v70, v[8:9], off
	v_or_b32_e32 v8, 0x3800, v48
	v_mov_b32_e32 v9, v49
	v_lshl_add_u64 v[24:25], v[2:3], 0, v[8:9]
	v_lshl_add_u64 v[8:9], v[4:5], 0, v[8:9]
	global_load_dword v71, v[24:25], off
	global_load_dword v72, v[8:9], off
	v_or_b32_e32 v8, 0x4000, v48
	v_mov_b32_e32 v9, v49
	v_lshl_add_u64 v[22:23], v[2:3], 0, v[8:9]
	v_lshl_add_u64 v[8:9], v[4:5], 0, v[8:9]
	global_load_dword v73, v[22:23], off
	global_load_dword v74, v[8:9], off
	v_or_b32_e32 v8, 0x4800, v48
	v_mov_b32_e32 v9, v49
	v_lshl_add_u64 v[20:21], v[2:3], 0, v[8:9]
	v_lshl_add_u64 v[8:9], v[4:5], 0, v[8:9]
	global_load_dword v46, v[20:21], off
	global_load_dword v47, v[8:9], off
	v_or_b32_e32 v8, 0x5000, v48
	v_mov_b32_e32 v9, v49
	v_lshl_add_u64 v[18:19], v[2:3], 0, v[8:9]
	v_lshl_add_u64 v[8:9], v[4:5], 0, v[8:9]
	global_load_dword v44, v[18:19], off
	global_load_dword v45, v[8:9], off
	v_or_b32_e32 v8, 0x5800, v48
	v_mov_b32_e32 v9, v49
	v_lshl_add_u64 v[16:17], v[2:3], 0, v[8:9]
	v_lshl_add_u64 v[8:9], v[4:5], 0, v[8:9]
	global_load_dword v42, v[16:17], off
	global_load_dword v43, v[8:9], off
	v_or_b32_e32 v8, 0x6000, v48
	v_mov_b32_e32 v9, v49
	v_lshl_add_u64 v[14:15], v[2:3], 0, v[8:9]
	v_lshl_add_u64 v[8:9], v[4:5], 0, v[8:9]
	global_load_dword v40, v[14:15], off
	global_load_dword v41, v[8:9], off
	v_or_b32_e32 v8, 0x6800, v48
	v_mov_b32_e32 v9, v49
	v_lshl_add_u64 v[12:13], v[2:3], 0, v[8:9]
	v_lshl_add_u64 v[8:9], v[4:5], 0, v[8:9]
	global_load_dword v38, v[12:13], off
	global_load_dword v39, v[8:9], off
	v_or_b32_e32 v8, 0x7000, v48
	v_mov_b32_e32 v9, v49
	v_lshl_add_u64 v[10:11], v[2:3], 0, v[8:9]
	v_lshl_add_u64 v[8:9], v[4:5], 0, v[8:9]
	v_or_b32_e32 v48, 0x7800, v48
	global_load_dword v36, v[10:11], off
	global_load_dword v37, v[8:9], off
	v_lshl_add_u64 v[8:9], v[2:3], 0, v[48:49]
	v_lshl_add_u64 v[48:49], v[4:5], 0, v[48:49]
	global_load_dword v34, v[8:9], off
	global_load_dword v35, v[48:49], off
	s_waitcnt vmcnt(0)
; template <int M> __device__ __forceinline__ float swz_xor(float v) { return __int_as_float(__builtin_amdgcn_ds_swizzle(__float_as_int(v), 0x1F | (M << 10))); }
; __device__ __forceinline__ float half_sum32(float v) { v += swz_xor<1>(v); v += swz_xor<2>(v); v += swz_xor<4>(v); v += swz_xor<8>(v); v += swz_xor<16>(v); return v; }
; __device__ __forceinline__ void diffmix_block(const Grp& G, int b, int h, int qb, float lam, const float* subln, int tid) {
;     ...
;             const float v0 = bflo(a[r]) - lam * bflo(c[r]), v1 = bfhi(a[r]) - lam * bfhi(c[r]);
;             const float ss = wave_sum(v0 * v0 + v1 * v1);
	v_lshlrev_b32_e32 v80, 16, v57
	v_lshlrev_b32_e32 v82, 16, v59
	v_lshlrev_b32_e32 v84, 16, v61
	v_lshlrev_b32_e32 v86, 16, v63
	v_lshlrev_b32_e32 v88, 16, v65
	v_lshlrev_b32_e32 v90, 16, v67
	v_lshlrev_b32_e32 v92, 16, v69
	v_lshlrev_b32_e32 v94, 16, v71
	v_lshlrev_b32_e32 v96, 16, v73
	v_lshlrev_b32_e32 v98, 16, v46
	v_lshlrev_b32_e32 v100, 16, v44
	v_lshlrev_b32_e32 v102, 16, v42
	v_lshlrev_b32_e32 v104, 16, v40
	v_lshlrev_b32_e32 v106, 16, v38
	v_lshlrev_b32_e32 v108, 16, v36
	v_lshlrev_b32_e32 v110, 16, v34
	v_lshlrev_b32_e32 v144, 16, v58
	v_lshlrev_b32_e32 v146, 16, v60
	v_lshlrev_b32_e32 v148, 16, v62
	v_lshlrev_b32_e32 v150, 16, v64
	v_lshlrev_b32_e32 v156, 16, v66
	v_lshlrev_b32_e32 v158, 16, v68
	v_lshlrev_b32_e32 v160, 16, v70
	v_lshlrev_b32_e32 v162, 16, v72
	v_lshlrev_b32_e32 v164, 16, v74
	v_lshlrev_b32_e32 v166, 16, v47
	v_lshlrev_b32_e32 v168, 16, v45
	v_lshlrev_b32_e32 v170, 16, v43
	v_lshlrev_b32_e32 v172, 16, v41
	v_lshlrev_b32_e32 v174, 16, v39
	v_lshlrev_b32_e32 v176, 16, v37
	v_lshlrev_b32_e32 v178, 16, v35
	v_and_b32_e32 v81, 0xffff0000, v57
	v_and_b32_e32 v83, 0xffff0000, v59
	v_and_b32_e32 v85, 0xffff0000, v61
	v_and_b32_e32 v87, 0xffff0000, v63
	v_and_b32_e32 v89, 0xffff0000, v65
	v_and_b32_e32 v91, 0xffff0000, v67
	v_and_b32_e32 v93, 0xffff0000, v69
	v_and_b32_e32 v95, 0xffff0000, v71
	v_and_b32_e32 v97, 0xffff0000, v73
	v_and_b32_e32 v99, 0xffff0000, v46
	v_and_b32_e32 v101, 0xffff0000, v44
	v_and_b32_e32 v103, 0xffff0000, v42
	v_and_b32_e32 v105, 0xffff0000, v40
	v_and_b32_e32 v107, 0xffff0000, v38
	v_and_b32_e32 v109, 0xffff0000, v36
	v_and_b32_e32 v111, 0xffff0000, v34
	v_and_b32_e32 v145, 0xffff0000, v58
	v_and_b32_e32 v147, 0xffff0000, v60
	v_and_b32_e32 v149, 0xffff0000, v62
	v_and_b32_e32 v151, 0xffff0000, v64
	v_and_b32_e32 v157, 0xffff0000, v66
	v_and_b32_e32 v159, 0xffff0000, v68
	v_and_b32_e32 v161, 0xffff0000, v70
	v_and_b32_e32 v163, 0xffff0000, v72
	v_and_b32_e32 v165, 0xffff0000, v74
	v_and_b32_e32 v167, 0xffff0000, v47
	v_and_b32_e32 v169, 0xffff0000, v45
	v_and_b32_e32 v171, 0xffff0000, v43
	v_and_b32_e32 v173, 0xffff0000, v41
	v_and_b32_e32 v175, 0xffff0000, v39
	v_and_b32_e32 v177, 0xffff0000, v37
	v_and_b32_e32 v179, 0xffff0000, v35
	v_pk_fma_f32 v[80:81], v[192:193], v[144:145], v[80:81] neg_lo:[1,0,0] neg_hi:[1,0,0]
	v_pk_fma_f32 v[82:83], v[192:193], v[146:147], v[82:83] neg_lo:[1,0,0] neg_hi:[1,0,0]
	v_pk_fma_f32 v[84:85], v[192:193], v[148:149], v[84:85] neg_lo:[1,0,0] neg_hi:[1,0,0]
	v_pk_fma_f32 v[86:87], v[192:193], v[150:151], v[86:87] neg_lo:[1,0,0] neg_hi:[1,0,0]
	v_pk_fma_f32 v[88:89], v[192:193], v[156:157], v[88:89] neg_lo:[1,0,0] neg_hi:[1,0,0]
	v_pk_fma_f32 v[90:91], v[192:193], v[158:159], v[90:91] neg_lo:[1,0,0] neg_hi:[1,0,0]
	v_pk_fma_f32 v[92:93], v[192:193], v[160:161], v[92:93] neg_lo:[1,0,0] neg_hi:[1,0,0]
	v_pk_fma_f32 v[94:95], v[192:193], v[162:163], v[94:95] neg_lo:[1,0,0] neg_hi:[1,0,0]
	v_pk_fma_f32 v[96:97], v[192:193], v[164:165], v[96:97] neg_lo:[1,0,0] neg_hi:[1,0,0]
	v_pk_fma_f32 v[98:99], v[192:193], v[166:167], v[98:99] neg_lo:[1,0,0] neg_hi:[1,0,0]
	v_pk_fma_f32 v[100:101], v[192:193], v[168:169], v[100:101] neg_lo:[1,0,0] neg_hi:[1,0,0]
	v_pk_fma_f32 v[102:103], v[192:193], v[170:171], v[102:103] neg_lo:[1,0,0] neg_hi:[1,0,0]
	v_pk_fma_f32 v[104:105], v[192:193], v[172:173], v[104:105] neg_lo:[1,0,0] neg_hi:[1,0,0]
	v_pk_fma_f32 v[106:107], v[192:193], v[174:175], v[106:107] neg_lo:[1,0,0] neg_hi:[1,0,0]
	v_pk_fma_f32 v[108:109], v[192:193], v[176:177], v[108:109] neg_lo:[1,0,0] neg_hi:[1,0,0]
	v_pk_fma_f32 v[110:111], v[192:193], v[178:179], v[110:111] neg_lo:[1,0,0] neg_hi:[1,0,0]
	v_pk_mul_f32 v[144:145], v[80:81], v[80:81]
	v_pk_mul_f32 v[146:147], v[82:83], v[82:83]
	v_pk_mul_f32 v[148:149], v[84:85], v[84:85]
	v_pk_mul_f32 v[150:151], v[86:87], v[86:87]
	v_pk_mul_f32 v[156:157], v[88:89], v[88:89]
	v_pk_mul_f32 v[158:159], v[90:91], v[90:91]
	v_pk_mul_f32 v[160:161], v[92:93], v[92:93]
	v_pk_mul_f32 v[162:163], v[94:95], v[94:95]
	v_pk_mul_f32 v[164:165], v[96:97], v[96:97]
	v_pk_mul_f32 v[166:167], v[98:99], v[98:99]
	v_pk_mul_f32 v[168:169], v[100:101], v[100:101]
	v_pk_mul_f32 v[170:171], v[102:103], v[102:103]
	v_pk_mul_f32 v[172:173], v[104:105], v[104:105]
	v_pk_mul_f32 v[174:175], v[106:107], v[106:107]
	v_pk_mul_f32 v[176:177], v[108:109], v[108:109]
	v_pk_mul_f32 v[178:179], v[110:111], v[110:111]
	v_add_f32_e32 v112, v144, v145
	v_add_f32_e32 v114, v146, v147
	v_add_f32_e32 v116, v148, v149
	v_add_f32_e32 v118, v150, v151
	v_add_f32_e32 v120, v156, v157
	v_add_f32_e32 v122, v158, v159
	v_add_f32_e32 v124, v160, v161
	v_add_f32_e32 v126, v162, v163
	v_add_f32_e32 v128, v164, v165
	v_add_f32_e32 v130, v166, v167
	v_add_f32_e32 v132, v168, v169
	v_add_f32_e32 v134, v170, v171
	v_add_f32_e32 v136, v172, v173
	v_add_f32_e32 v138, v174, v175
	v_add_f32_e32 v140, v176, v177
	v_add_f32_e32 v142, v178, v179
	v_add_f32_dpp v112, v112, v112 quad_perm:[1,0,3,2] row_mask:0xf bank_mask:0xf
	v_add_f32_dpp v114, v114, v114 quad_perm:[1,0,3,2] row_mask:0xf bank_mask:0xf
	v_add_f32_dpp v116, v116, v116 quad_perm:[1,0,3,2] row_mask:0xf bank_mask:0xf
	v_add_f32_dpp v118, v118, v118 quad_perm:[1,0,3,2] row_mask:0xf bank_mask:0xf
	v_add_f32_dpp v120, v120, v120 quad_perm:[1,0,3,2] row_mask:0xf bank_mask:0xf
	v_add_f32_dpp v122, v122, v122 quad_perm:[1,0,3,2] row_mask:0xf bank_mask:0xf
	v_add_f32_dpp v124, v124, v124 quad_perm:[1,0,3,2] row_mask:0xf bank_mask:0xf
	v_add_f32_dpp v126, v126, v126 quad_perm:[1,0,3,2] row_mask:0xf bank_mask:0xf
	v_add_f32_dpp v128, v128, v128 quad_perm:[1,0,3,2] row_mask:0xf bank_mask:0xf
; template <int M> __device__ __forceinline__ float swz_xor(float v) { return __int_as_float(__builtin_amdgcn_ds_swizzle(__float_as_int(v), 0x1F | (M << 10))); }
; __device__ __forceinline__ float half_sum32(float v) { v += swz_xor<1>(v); v += swz_xor<2>(v); v += swz_xor<4>(v); v += swz_xor<8>(v); v += swz_xor<16>(v); return v; }
; __device__ __forceinline__ float wave_sum(float v) {
;     v = half_sum32(v);
;     auto rr = __builtin_amdgcn_permlane32_swap(__float_as_uint(v), __float_as_uint(v), false, false);
;     return __uint_as_float(rr[0]) + __uint_as_float(rr[1]);
	v_add_f32_dpp v130, v130, v130 quad_perm:[1,0,3,2] row_mask:0xf bank_mask:0xf
	v_add_f32_dpp v132, v132, v132 quad_perm:[1,0,3,2] row_mask:0xf bank_mask:0xf
	v_add_f32_dpp v134, v134, v134 quad_perm:[1,0,3,2] row_mask:0xf bank_mask:0xf
	v_add_f32_dpp v136, v136, v136 quad_perm:[1,0,3,2] row_mask:0xf bank_mask:0xf
	v_add_f32_dpp v138, v138, v138 quad_perm:[1,0,3,2] row_mask:0xf bank_mask:0xf
	v_add_f32_dpp v140, v140, v140 quad_perm:[1,0,3,2] row_mask:0xf bank_mask:0xf
	v_add_f32_dpp v142, v142, v142 quad_perm:[1,0,3,2] row_mask:0xf bank_mask:0xf
	v_add_f32_dpp v112, v112, v112 quad_perm:[2,3,0,1] row_mask:0xf bank_mask:0xf
	v_add_f32_dpp v114, v114, v114 quad_perm:[2,3,0,1] row_mask:0xf bank_mask:0xf
	v_add_f32_dpp v116, v116, v116 quad_perm:[2,3,0,1] row_mask:0xf bank_mask:0xf
	v_add_f32_dpp v118, v118, v118 quad_perm:[2,3,0,1] row_mask:0xf bank_mask:0xf
	v_add_f32_dpp v120, v120, v120 quad_perm:[2,3,0,1] row_mask:0xf bank_mask:0xf
	v_add_f32_dpp v122, v122, v122 quad_perm:[2,3,0,1] row_mask:0xf bank_mask:0xf
	v_add_f32_dpp v124, v124, v124 quad_perm:[2,3,0,1] row_mask:0xf bank_mask:0xf
	v_add_f32_dpp v126, v126, v126 quad_perm:[2,3,0,1] row_mask:0xf bank_mask:0xf
	v_add_f32_dpp v128, v128, v128 quad_perm:[2,3,0,1] row_mask:0xf bank_mask:0xf
	v_add_f32_dpp v130, v130, v130 quad_perm:[2,3,0,1] row_mask:0xf bank_mask:0xf
	v_add_f32_dpp v132, v132, v132 quad_perm:[2,3,0,1] row_mask:0xf bank_mask:0xf
	v_add_f32_dpp v134, v134, v134 quad_perm:[2,3,0,1] row_mask:0xf bank_mask:0xf
	v_add_f32_dpp v136, v136, v136 quad_perm:[2,3,0,1] row_mask:0xf bank_mask:0xf
	v_add_f32_dpp v138, v138, v138 quad_perm:[2,3,0,1] row_mask:0xf bank_mask:0xf
	v_add_f32_dpp v140, v140, v140 quad_perm:[2,3,0,1] row_mask:0xf bank_mask:0xf
	v_add_f32_dpp v142, v142, v142 quad_perm:[2,3,0,1] row_mask:0xf bank_mask:0xf
	v_add_f32_dpp v112, v112, v112 row_half_mirror row_mask:0xf bank_mask:0xf
	v_add_f32_dpp v114, v114, v114 row_half_mirror row_mask:0xf bank_mask:0xf
	v_add_f32_dpp v116, v116, v116 row_half_mirror row_mask:0xf bank_mask:0xf
	v_add_f32_dpp v118, v118, v118 row_half_mirror row_mask:0xf bank_mask:0xf
	v_add_f32_dpp v120, v120, v120 row_half_mirror row_mask:0xf bank_mask:0xf
	v_add_f32_dpp v122, v122, v122 row_half_mirror row_mask:0xf bank_mask:0xf
	v_add_f32_dpp v124, v124, v124 row_half_mirror row_mask:0xf bank_mask:0xf
	v_add_f32_dpp v126, v126, v126 row_half_mirror row_mask:0xf bank_mask:0xf
	v_add_f32_dpp v128, v128, v128 row_half_mirror row_mask:0xf bank_mask:0xf
	v_add_f32_dpp v130, v130, v130 row_half_mirror row_mask:0xf bank_mask:0xf
	v_add_f32_dpp v132, v132, v132 row_half_mirror row_mask:0xf bank_mask:0xf
	v_add_f32_dpp v134, v134, v134 row_half_mirror row_mask:0xf bank_mask:0xf
	v_add_f32_dpp v136, v136, v136 row_half_mirror row_mask:0xf bank_mask:0xf
	v_add_f32_dpp v138, v138, v138 row_half_mirror row_mask:0xf bank_mask:0xf
	v_add_f32_dpp v140, v140, v140 row_half_mirror row_mask:0xf bank_mask:0xf
	v_add_f32_dpp v142, v142, v142 row_half_mirror row_mask:0xf bank_mask:0xf
	v_add_f32_dpp v112, v112, v112 row_mirror row_mask:0xf bank_mask:0xf
	v_add_f32_dpp v114, v114, v114 row_mirror row_mask:0xf bank_mask:0xf
	v_add_f32_dpp v116, v116, v116 row_mirror row_mask:0xf bank_mask:0xf
	v_add_f32_dpp v118, v118, v118 row_mirror row_mask:0xf bank_mask:0xf
	v_add_f32_dpp v120, v120, v120 row_mirror row_mask:0xf bank_mask:0xf
	v_add_f32_dpp v122, v122, v122 row_mirror row_mask:0xf bank_mask:0xf
	v_add_f32_dpp v124, v124, v124 row_mirror row_mask:0xf bank_mask:0xf
	v_add_f32_dpp v126, v126, v126 row_mirror row_mask:0xf bank_mask:0xf
	v_add_f32_dpp v128, v128, v128 row_mirror row_mask:0xf bank_mask:0xf
	v_add_f32_dpp v130, v130, v130 row_mirror row_mask:0xf bank_mask:0xf
	v_add_f32_dpp v132, v132, v132 row_mirror row_mask:0xf bank_mask:0xf
	v_add_f32_dpp v134, v134, v134 row_mirror row_mask:0xf bank_mask:0xf
	v_add_f32_dpp v136, v136, v136 row_mirror row_mask:0xf bank_mask:0xf
	v_add_f32_dpp v138, v138, v138 row_mirror row_mask:0xf bank_mask:0xf
	v_add_f32_dpp v140, v140, v140 row_mirror row_mask:0xf bank_mask:0xf
	v_add_f32_dpp v142, v142, v142 row_mirror row_mask:0xf bank_mask:0xf
	v_mov_b32_e32 v144, v112
	v_mov_b32_e32 v146, v114
	v_mov_b32_e32 v148, v116
	v_mov_b32_e32 v150, v118
	v_mov_b32_e32 v156, v120
	v_mov_b32_e32 v158, v122
	v_mov_b32_e32 v160, v124
	v_mov_b32_e32 v162, v126
	v_mov_b32_e32 v164, v128
	v_mov_b32_e32 v166, v130
	v_mov_b32_e32 v168, v132
	v_mov_b32_e32 v170, v134
	v_mov_b32_e32 v172, v136
	v_mov_b32_e32 v174, v138
	v_mov_b32_e32 v176, v140
	v_mov_b32_e32 v178, v142
	v_permlane16_swap_b32_e32 v112, v144
	v_permlane16_swap_b32_e32 v114, v146
	v_permlane16_swap_b32_e32 v116, v148
	v_permlane16_swap_b32_e32 v118, v150
	v_permlane16_swap_b32_e32 v120, v156
	v_permlane16_swap_b32_e32 v122, v158
	v_permlane16_swap_b32_e32 v124, v160
	v_permlane16_swap_b32_e32 v126, v162
	v_permlane16_swap_b32_e32 v128, v164
	v_permlane16_swap_b32_e32 v130, v166
	v_permlane16_swap_b32_e32 v132, v168
	v_permlane16_swap_b32_e32 v134, v170
	v_permlane16_swap_b32_e32 v136, v172
	v_permlane16_swap_b32_e32 v138, v174
	v_permlane16_swap_b32_e32 v140, v176
	v_permlane16_swap_b32_e32 v142, v178
	v_add_f32_e32 v112, v112, v144
	v_add_f32_e32 v114, v114, v146
	v_add_f32_e32 v116, v116, v148
	v_add_f32_e32 v118, v118, v150
	v_add_f32_e32 v120, v120, v156
	v_add_f32_e32 v122, v122, v158
	v_add_f32_e32 v124, v124, v160
	v_add_f32_e32 v126, v126, v162
	v_add_f32_e32 v128, v128, v164
	v_add_f32_e32 v130, v130, v166
	v_add_f32_e32 v132, v132, v168
	v_add_f32_e32 v134, v134, v170
	v_add_f32_e32 v136, v136, v172
	v_add_f32_e32 v138, v138, v174
	v_add_f32_e32 v140, v140, v176
; __device__ __forceinline__ float half_sum32(float v) { v += swz_xor<1>(v); v += swz_xor<2>(v); v += swz_xor<4>(v); v += swz_xor<8>(v); v += swz_xor<16>(v); return v; }
; __device__ __forceinline__ unsigned pk2(float lo, float hi) { f32x2 v = {lo, hi}; bf16x2_hw b = __builtin_convertvector(v, bf16x2_hw); return __builtin_bit_cast(unsigned, b); }
; __device__ __forceinline__ float wave_sum(float v) {
;     v = half_sum32(v);
;     auto rr = __builtin_amdgcn_permlane32_swap(__float_as_uint(v), __float_as_uint(v), false, false);
;     return __uint_as_float(rr[0]) + __uint_as_float(rr[1]);
; __device__ __forceinline__ void diffmix_block(const Grp& G, int b, int h, int qb, float lam, const float* subln, int tid) {
;     ...
;             const float rs = 1.0f / sqrtf(ss * (1.f / 128.f) + EPSN);
;             *((unsigned*)(G.DO + (row0 + rb + r) * 1024 + h * 128) + lane) = pk2(v0 * rs * g0, v1 * rs * g1);
	v_add_f32_e32 v142, v142, v178
	v_mov_b32_e32 v144, v112
	v_mov_b32_e32 v146, v114
	v_mov_b32_e32 v148, v116
	v_mov_b32_e32 v150, v118
	v_mov_b32_e32 v156, v120
	v_mov_b32_e32 v158, v122
	v_mov_b32_e32 v160, v124
	v_mov_b32_e32 v162, v126
	v_mov_b32_e32 v164, v128
	v_mov_b32_e32 v166, v130
	v_mov_b32_e32 v168, v132
	v_mov_b32_e32 v170, v134
	v_mov_b32_e32 v172, v136
	v_mov_b32_e32 v174, v138
	v_mov_b32_e32 v176, v140
	v_mov_b32_e32 v178, v142
	v_permlane32_swap_b32_e32 v112, v144
	v_permlane32_swap_b32_e32 v114, v146
	v_permlane32_swap_b32_e32 v116, v148
	v_permlane32_swap_b32_e32 v118, v150
	v_permlane32_swap_b32_e32 v120, v156
	v_permlane32_swap_b32_e32 v122, v158
	v_permlane32_swap_b32_e32 v124, v160
	v_permlane32_swap_b32_e32 v126, v162
	v_permlane32_swap_b32_e32 v128, v164
	v_permlane32_swap_b32_e32 v130, v166
	v_permlane32_swap_b32_e32 v132, v168
	v_permlane32_swap_b32_e32 v134, v170
	v_permlane32_swap_b32_e32 v136, v172
	v_permlane32_swap_b32_e32 v138, v174
	v_permlane32_swap_b32_e32 v140, v176
	v_permlane32_swap_b32_e32 v142, v178
	v_add_f32_e32 v112, v112, v144
	v_add_f32_e32 v114, v114, v146
	v_add_f32_e32 v116, v116, v148
	v_add_f32_e32 v118, v118, v150
	v_add_f32_e32 v120, v120, v156
	v_add_f32_e32 v122, v122, v158
	v_add_f32_e32 v124, v124, v160
	v_add_f32_e32 v126, v126, v162
	v_add_f32_e32 v128, v128, v164
	v_add_f32_e32 v130, v130, v166
	v_add_f32_e32 v132, v132, v168
	v_add_f32_e32 v134, v134, v170
	v_add_f32_e32 v136, v136, v172
	v_add_f32_e32 v138, v138, v174
	v_add_f32_e32 v140, v140, v176
	v_add_f32_e32 v142, v142, v178
	v_fmamk_f32 v112, v112, 0x3c000000, v205
	v_cmp_gt_f32_e32 vcc, s63, v112
	v_mul_f32_e32 v180, 0x4f800000, v112
	s_nop 0
	v_cndmask_b32_e32 v112, v112, v180, vcc
	v_sqrt_f32_e32 v180, v112
	s_nop 0
	v_add_u32_e32 v181, -1, v180
	v_fma_f32 v182, -v181, v180, v112
	v_cmp_ge_f32_e64 s[0:1], 0, v182
	v_add_u32_e32 v182, 1, v180
	s_nop 0
	v_cndmask_b32_e64 v181, v180, v181, s[0:1]
	v_fma_f32 v180, -v182, v180, v112
	v_cmp_lt_f32_e64 s[0:1], 0, v180
	s_nop 1
	v_cndmask_b32_e64 v180, v181, v182, s[0:1]
	v_mul_f32_e32 v181, 0x37800000, v180
	v_cndmask_b32_e32 v180, v180, v181, vcc
	v_cmp_class_f32_e32 vcc, v112, v206
	s_nop 1
	v_cndmask_b32_e32 v112, v180, v112, vcc
	v_rcp_f32_e32 v112, v112
	s_nop 0
	v_pk_mul_f32 v[80:81], v[80:81], v[112:113] op_sel_hi:[1,0]
	s_nop 0
	v_pk_mul_f32 v[80:81], v[0:1], v[80:81]
	s_nop 0
	v_cvt_pk_bf16_f32 v80, v80, v81
	global_store_dword v[50:51], v80, off
	v_fmamk_f32 v114, v114, 0x3c000000, v205
	v_cmp_gt_f32_e32 vcc, s63, v114
	v_mul_f32_e32 v180, 0x4f800000, v114
	s_nop 0
	v_cndmask_b32_e32 v114, v114, v180, vcc
	v_sqrt_f32_e32 v180, v114
	s_nop 0
	v_add_u32_e32 v181, -1, v180
	v_fma_f32 v182, -v181, v180, v114
	v_cmp_ge_f32_e64 s[0:1], 0, v182
	v_add_u32_e32 v182, 1, v180
	s_nop 0
	v_cndmask_b32_e64 v181, v180, v181, s[0:1]
	v_fma_f32 v180, -v182, v180, v114
	v_cmp_lt_f32_e64 s[0:1], 0, v180
	s_nop 1
	v_cndmask_b32_e64 v180, v181, v182, s[0:1]
	v_mul_f32_e32 v181, 0x37800000, v180
	v_cndmask_b32_e32 v180, v180, v181, vcc
	v_cmp_class_f32_e32 vcc, v114, v206
	s_nop 1
	v_cndmask_b32_e32 v114, v180, v114, vcc
	v_rcp_f32_e32 v114, v114
	s_nop 0
	v_pk_mul_f32 v[82:83], v[82:83], v[114:115] op_sel_hi:[1,0]
	s_nop 0
	v_pk_mul_f32 v[82:83], v[0:1], v[82:83]
	s_nop 0
	v_cvt_pk_bf16_f32 v82, v82, v83
	global_store_dword v[52:53], v82, off
	v_fmamk_f32 v116, v116, 0x3c000000, v205
	v_cmp_gt_f32_e32 vcc, s63, v116
	v_mul_f32_e32 v180, 0x4f800000, v116
	s_nop 0
	v_cndmask_b32_e32 v116, v116, v180, vcc
	v_sqrt_f32_e32 v180, v116
	s_nop 0
	v_add_u32_e32 v181, -1, v180
	v_fma_f32 v182, -v181, v180, v116
	v_cmp_ge_f32_e64 s[0:1], 0, v182
	v_add_u32_e32 v182, 1, v180
	s_nop 0
	v_cndmask_b32_e64 v181, v180, v181, s[0:1]
	v_fma_f32 v180, -v182, v180, v116
	v_cmp_lt_f32_e64 s[0:1], 0, v180
	s_nop 1
	v_cndmask_b32_e64 v180, v181, v182, s[0:1]
	v_mul_f32_e32 v181, 0x37800000, v180
	v_cndmask_b32_e32 v180, v180, v181, vcc
	v_cmp_class_f32_e32 vcc, v116, v206
	s_nop 1
	v_cndmask_b32_e32 v116, v180, v116, vcc
	v_rcp_f32_e32 v116, v116
	s_nop 0
	v_pk_mul_f32 v[84:85], v[84:85], v[116:117] op_sel_hi:[1,0]
	s_nop 0
	v_pk_mul_f32 v[84:85], v[0:1], v[84:85]
	s_nop 0
	v_cvt_pk_bf16_f32 v84, v84, v85
	global_store_dword v[54:55], v84, off
	v_fmamk_f32 v118, v118, 0x3c000000, v205
	v_cmp_gt_f32_e32 vcc, s63, v118
	v_mul_f32_e32 v180, 0x4f800000, v118
	s_nop 0
	v_cndmask_b32_e32 v118, v118, v180, vcc
	v_sqrt_f32_e32 v180, v118
	s_nop 0
	v_add_u32_e32 v181, -1, v180
	v_fma_f32 v182, -v181, v180, v118
	v_cmp_ge_f32_e64 s[0:1], 0, v182
	v_add_u32_e32 v182, 1, v180
	s_nop 0
	v_cndmask_b32_e64 v181, v180, v181, s[0:1]
	v_fma_f32 v180, -v182, v180, v118
	v_cmp_lt_f32_e64 s[0:1], 0, v180
	s_nop 1
	v_cndmask_b32_e64 v180, v181, v182, s[0:1]
	v_mul_f32_e32 v181, 0x37800000, v180
	v_cndmask_b32_e32 v180, v180, v181, vcc
	v_cmp_class_f32_e32 vcc, v118, v206
	s_nop 1
	v_cndmask_b32_e32 v118, v180, v118, vcc
	v_rcp_f32_e32 v118, v118
	s_nop 0
	v_pk_mul_f32 v[86:87], v[86:87], v[118:119] op_sel_hi:[1,0]
	s_nop 0
	v_pk_mul_f32 v[86:87], v[0:1], v[86:87]
	s_nop 0
	v_cvt_pk_bf16_f32 v86, v86, v87
	global_store_dword v[32:33], v86, off
	v_fmamk_f32 v120, v120, 0x3c000000, v205
	v_cmp_gt_f32_e32 vcc, s63, v120
	v_mul_f32_e32 v180, 0x4f800000, v120
	s_nop 0
	v_cndmask_b32_e32 v120, v120, v180, vcc
	v_sqrt_f32_e32 v180, v120
	s_nop 0
	v_add_u32_e32 v181, -1, v180
	v_fma_f32 v182, -v181, v180, v120
	v_cmp_ge_f32_e64 s[0:1], 0, v182
	v_add_u32_e32 v182, 1, v180
	s_nop 0
	v_cndmask_b32_e64 v181, v180, v181, s[0:1]
	v_fma_f32 v180, -v182, v180, v120
	v_cmp_lt_f32_e64 s[0:1], 0, v180
	s_nop 1
	v_cndmask_b32_e64 v180, v181, v182, s[0:1]
; __device__ __forceinline__ unsigned pk2(float lo, float hi) { f32x2 v = {lo, hi}; bf16x2_hw b = __builtin_convertvector(v, bf16x2_hw); return __builtin_bit_cast(unsigned, b); }
; __device__ __forceinline__ void diffmix_block(const Grp& G, int b, int h, int qb, float lam, const float* subln, int tid) {
;     ...
;             const float rs = 1.0f / sqrtf(ss * (1.f / 128.f) + EPSN);
;             *((unsigned*)(G.DO + (row0 + rb + r) * 1024 + h * 128) + lane) = pk2(v0 * rs * g0, v1 * rs * g1);
	v_mul_f32_e32 v181, 0x37800000, v180
	v_cndmask_b32_e32 v180, v180, v181, vcc
	v_cmp_class_f32_e32 vcc, v120, v206
	s_nop 1
	v_cndmask_b32_e32 v120, v180, v120, vcc
	v_rcp_f32_e32 v120, v120
	s_nop 0
	v_pk_mul_f32 v[88:89], v[88:89], v[120:121] op_sel_hi:[1,0]
	s_nop 0
	v_pk_mul_f32 v[88:89], v[0:1], v[88:89]
	s_nop 0
	v_cvt_pk_bf16_f32 v88, v88, v89
	global_store_dword v[30:31], v88, off
	v_fmamk_f32 v122, v122, 0x3c000000, v205
	v_cmp_gt_f32_e32 vcc, s63, v122
	v_mul_f32_e32 v180, 0x4f800000, v122
	s_nop 0
	v_cndmask_b32_e32 v122, v122, v180, vcc
	v_sqrt_f32_e32 v180, v122
	s_nop 0
	v_add_u32_e32 v181, -1, v180
	v_fma_f32 v182, -v181, v180, v122
	v_cmp_ge_f32_e64 s[0:1], 0, v182
	v_add_u32_e32 v182, 1, v180
	s_nop 0
	v_cndmask_b32_e64 v181, v180, v181, s[0:1]
	v_fma_f32 v180, -v182, v180, v122
	v_cmp_lt_f32_e64 s[0:1], 0, v180
	s_nop 1
	v_cndmask_b32_e64 v180, v181, v182, s[0:1]
	v_mul_f32_e32 v181, 0x37800000, v180
	v_cndmask_b32_e32 v180, v180, v181, vcc
	v_cmp_class_f32_e32 vcc, v122, v206
	s_nop 1
	v_cndmask_b32_e32 v122, v180, v122, vcc
	v_rcp_f32_e32 v122, v122
	s_nop 0
	v_pk_mul_f32 v[90:91], v[90:91], v[122:123] op_sel_hi:[1,0]
	s_nop 0
	v_pk_mul_f32 v[90:91], v[0:1], v[90:91]
	s_nop 0
	v_cvt_pk_bf16_f32 v90, v90, v91
	global_store_dword v[28:29], v90, off
	v_fmamk_f32 v124, v124, 0x3c000000, v205
	v_cmp_gt_f32_e32 vcc, s63, v124
	v_mul_f32_e32 v180, 0x4f800000, v124
	s_nop 0
	v_cndmask_b32_e32 v124, v124, v180, vcc
	v_sqrt_f32_e32 v180, v124
	s_nop 0
	v_add_u32_e32 v181, -1, v180
	v_fma_f32 v182, -v181, v180, v124
	v_cmp_ge_f32_e64 s[0:1], 0, v182
	v_add_u32_e32 v182, 1, v180
	s_nop 0
	v_cndmask_b32_e64 v181, v180, v181, s[0:1]
	v_fma_f32 v180, -v182, v180, v124
	v_cmp_lt_f32_e64 s[0:1], 0, v180
	s_nop 1
	v_cndmask_b32_e64 v180, v181, v182, s[0:1]
	v_mul_f32_e32 v181, 0x37800000, v180
	v_cndmask_b32_e32 v180, v180, v181, vcc
	v_cmp_class_f32_e32 vcc, v124, v206
	s_nop 1
	v_cndmask_b32_e32 v124, v180, v124, vcc
	v_rcp_f32_e32 v124, v124
	s_nop 0
	v_pk_mul_f32 v[92:93], v[92:93], v[124:125] op_sel_hi:[1,0]
	s_nop 0
	v_pk_mul_f32 v[92:93], v[0:1], v[92:93]
	s_nop 0
	v_cvt_pk_bf16_f32 v92, v92, v93
	global_store_dword v[26:27], v92, off
	v_fmamk_f32 v126, v126, 0x3c000000, v205
	v_cmp_gt_f32_e32 vcc, s63, v126
	v_mul_f32_e32 v180, 0x4f800000, v126
	s_nop 0
	v_cndmask_b32_e32 v126, v126, v180, vcc
	v_sqrt_f32_e32 v180, v126
	s_nop 0
	v_add_u32_e32 v181, -1, v180
	v_fma_f32 v182, -v181, v180, v126
	v_cmp_ge_f32_e64 s[0:1], 0, v182
	v_add_u32_e32 v182, 1, v180
	s_nop 0
	v_cndmask_b32_e64 v181, v180, v181, s[0:1]
	v_fma_f32 v180, -v182, v180, v126
	v_cmp_lt_f32_e64 s[0:1], 0, v180
	s_nop 1
	v_cndmask_b32_e64 v180, v181, v182, s[0:1]
	v_mul_f32_e32 v181, 0x37800000, v180
	v_cndmask_b32_e32 v180, v180, v181, vcc
	v_cmp_class_f32_e32 vcc, v126, v206
	s_nop 1
	v_cndmask_b32_e32 v126, v180, v126, vcc
	v_rcp_f32_e32 v126, v126
	s_nop 0
	v_pk_mul_f32 v[94:95], v[94:95], v[126:127] op_sel_hi:[1,0]
	s_nop 0
	v_pk_mul_f32 v[94:95], v[0:1], v[94:95]
	s_nop 0
	v_cvt_pk_bf16_f32 v94, v94, v95
	global_store_dword v[24:25], v94, off
	v_fmamk_f32 v128, v128, 0x3c000000, v205
	v_cmp_gt_f32_e32 vcc, s63, v128
	v_mul_f32_e32 v180, 0x4f800000, v128
	s_nop 0
	v_cndmask_b32_e32 v128, v128, v180, vcc
	v_sqrt_f32_e32 v180, v128
	s_nop 0
	v_add_u32_e32 v181, -1, v180
	v_fma_f32 v182, -v181, v180, v128
	v_cmp_ge_f32_e64 s[0:1], 0, v182
	v_add_u32_e32 v182, 1, v180
	s_nop 0
	v_cndmask_b32_e64 v181, v180, v181, s[0:1]
	v_fma_f32 v180, -v182, v180, v128
	v_cmp_lt_f32_e64 s[0:1], 0, v180
	s_nop 1
	v_cndmask_b32_e64 v180, v181, v182, s[0:1]
	v_mul_f32_e32 v181, 0x37800000, v180
	v_cndmask_b32_e32 v180, v180, v181, vcc
	v_cmp_class_f32_e32 vcc, v128, v206
	s_nop 1
	v_cndmask_b32_e32 v128, v180, v128, vcc
	v_rcp_f32_e32 v128, v128
	s_nop 0
	v_pk_mul_f32 v[96:97], v[96:97], v[128:129] op_sel_hi:[1,0]
	s_nop 0
	v_pk_mul_f32 v[96:97], v[0:1], v[96:97]
	s_nop 0
	v_cvt_pk_bf16_f32 v96, v96, v97
	global_store_dword v[22:23], v96, off
	v_fmamk_f32 v130, v130, 0x3c000000, v205
	v_cmp_gt_f32_e32 vcc, s63, v130
	v_mul_f32_e32 v180, 0x4f800000, v130
	s_nop 0
	v_cndmask_b32_e32 v130, v130, v180, vcc
	v_sqrt_f32_e32 v180, v130
	s_nop 0
	v_add_u32_e32 v181, -1, v180
	v_fma_f32 v182, -v181, v180, v130
	v_cmp_ge_f32_e64 s[0:1], 0, v182
	v_add_u32_e32 v182, 1, v180
	s_nop 0
	v_cndmask_b32_e64 v181, v180, v181, s[0:1]
	v_fma_f32 v180, -v182, v180, v130
	v_cmp_lt_f32_e64 s[0:1], 0, v180
	s_nop 1
	v_cndmask_b32_e64 v180, v181, v182, s[0:1]
	v_mul_f32_e32 v181, 0x37800000, v180
	v_cndmask_b32_e32 v180, v180, v181, vcc
	v_cmp_class_f32_e32 vcc, v130, v206
	s_nop 1
	v_cndmask_b32_e32 v130, v180, v130, vcc
	v_rcp_f32_e32 v130, v130
	s_nop 0
	v_pk_mul_f32 v[98:99], v[98:99], v[130:131] op_sel_hi:[1,0]
	s_nop 0
	v_pk_mul_f32 v[98:99], v[0:1], v[98:99]
	s_nop 0
	v_cvt_pk_bf16_f32 v98, v98, v99
	global_store_dword v[20:21], v98, off
	v_fmamk_f32 v132, v132, 0x3c000000, v205
	v_cmp_gt_f32_e32 vcc, s63, v132
	v_mul_f32_e32 v180, 0x4f800000, v132
	s_nop 0
	v_cndmask_b32_e32 v132, v132, v180, vcc
	v_sqrt_f32_e32 v180, v132
	s_nop 0
	v_add_u32_e32 v181, -1, v180
	v_fma_f32 v182, -v181, v180, v132
	v_cmp_ge_f32_e64 s[0:1], 0, v182
	v_add_u32_e32 v182, 1, v180
	s_nop 0
	v_cndmask_b32_e64 v181, v180, v181, s[0:1]
	v_fma_f32 v180, -v182, v180, v132
	v_cmp_lt_f32_e64 s[0:1], 0, v180
	s_nop 1
	v_cndmask_b32_e64 v180, v181, v182, s[0:1]
	v_mul_f32_e32 v181, 0x37800000, v180
	v_cndmask_b32_e32 v180, v180, v181, vcc
	v_cmp_class_f32_e32 vcc, v132, v206
	s_nop 1
	v_cndmask_b32_e32 v132, v180, v132, vcc
	v_rcp_f32_e32 v132, v132
	s_nop 0
	v_pk_mul_f32 v[100:101], v[100:101], v[132:133] op_sel_hi:[1,0]
; __device__ __forceinline__ unsigned pk2(float lo, float hi) { f32x2 v = {lo, hi}; bf16x2_hw b = __builtin_convertvector(v, bf16x2_hw); return __builtin_bit_cast(unsigned, b); }
; __device__ __forceinline__ void diffmix_block(const Grp& G, int b, int h, int qb, float lam, const float* subln, int tid) {
;     ...
;             const float rs = 1.0f / sqrtf(ss * (1.f / 128.f) + EPSN);
;             *((unsigned*)(G.DO + (row0 + rb + r) * 1024 + h * 128) + lane) = pk2(v0 * rs * g0, v1 * rs * g1);
; __device__ __forceinline__ void phase_attention(const Args& a, const Grp& G, LAS unsigned char* lds, const int tid_in) {
;     ...
;             for (int r = 0; r < GBATCH * 8 / 64; ++r) { const int bh = r * 64 + (v >> 2), b = bh >> 3, h = bh & 7;
;                 for (int n = 0; n < 2; ++n)
;                     for (int i = 0; i < 2; ++i) attn_unit_coop<true>(G, b, h, i ? p : 7 - p, n, lds, tid_in);
;                 asm volatile("s_waitcnt vmcnt(0)" ::: "memory"); __syncthreads();
;                 int t2 = tid_in; asm volatile("" : "+v"(t2));
;                 diffmix_block(G, b, h, 7 - p, lam, subln, t2); diffmix_block(G, b, h, p, lam, subln, t2); }
	s_nop 0
	v_pk_mul_f32 v[100:101], v[0:1], v[100:101]
	s_nop 0
	v_cvt_pk_bf16_f32 v100, v100, v101
	global_store_dword v[18:19], v100, off
	v_fmamk_f32 v134, v134, 0x3c000000, v205
	v_cmp_gt_f32_e32 vcc, s63, v134
	v_mul_f32_e32 v180, 0x4f800000, v134
	s_nop 0
	v_cndmask_b32_e32 v134, v134, v180, vcc
	v_sqrt_f32_e32 v180, v134
	s_nop 0
	v_add_u32_e32 v181, -1, v180
	v_fma_f32 v182, -v181, v180, v134
	v_cmp_ge_f32_e64 s[0:1], 0, v182
	v_add_u32_e32 v182, 1, v180
	s_nop 0
	v_cndmask_b32_e64 v181, v180, v181, s[0:1]
	v_fma_f32 v180, -v182, v180, v134
	v_cmp_lt_f32_e64 s[0:1], 0, v180
	s_nop 1
	v_cndmask_b32_e64 v180, v181, v182, s[0:1]
	v_mul_f32_e32 v181, 0x37800000, v180
	v_cndmask_b32_e32 v180, v180, v181, vcc
	v_cmp_class_f32_e32 vcc, v134, v206
	s_nop 1
	v_cndmask_b32_e32 v134, v180, v134, vcc
	v_rcp_f32_e32 v134, v134
	s_nop 0
	v_pk_mul_f32 v[102:103], v[102:103], v[134:135] op_sel_hi:[1,0]
	s_nop 0
	v_pk_mul_f32 v[102:103], v[0:1], v[102:103]
	s_nop 0
	v_cvt_pk_bf16_f32 v102, v102, v103
	global_store_dword v[16:17], v102, off
	v_fmamk_f32 v136, v136, 0x3c000000, v205
	v_cmp_gt_f32_e32 vcc, s63, v136
	v_mul_f32_e32 v180, 0x4f800000, v136
	s_nop 0
	v_cndmask_b32_e32 v136, v136, v180, vcc
	v_sqrt_f32_e32 v180, v136
	s_nop 0
	v_add_u32_e32 v181, -1, v180
	v_fma_f32 v182, -v181, v180, v136
	v_cmp_ge_f32_e64 s[0:1], 0, v182
	v_add_u32_e32 v182, 1, v180
	s_nop 0
	v_cndmask_b32_e64 v181, v180, v181, s[0:1]
	v_fma_f32 v180, -v182, v180, v136
	v_cmp_lt_f32_e64 s[0:1], 0, v180
	s_nop 1
	v_cndmask_b32_e64 v180, v181, v182, s[0:1]
	v_mul_f32_e32 v181, 0x37800000, v180
	v_cndmask_b32_e32 v180, v180, v181, vcc
	v_cmp_class_f32_e32 vcc, v136, v206
	s_nop 1
	v_cndmask_b32_e32 v136, v180, v136, vcc
	v_rcp_f32_e32 v136, v136
	s_nop 0
	v_pk_mul_f32 v[104:105], v[104:105], v[136:137] op_sel_hi:[1,0]
	s_nop 0
	v_pk_mul_f32 v[104:105], v[0:1], v[104:105]
	s_nop 0
	v_cvt_pk_bf16_f32 v104, v104, v105
	global_store_dword v[14:15], v104, off
	v_fmamk_f32 v138, v138, 0x3c000000, v205
	v_cmp_gt_f32_e32 vcc, s63, v138
	v_mul_f32_e32 v180, 0x4f800000, v138
	s_nop 0
	v_cndmask_b32_e32 v138, v138, v180, vcc
	v_sqrt_f32_e32 v180, v138
	s_nop 0
	v_add_u32_e32 v181, -1, v180
	v_fma_f32 v182, -v181, v180, v138
	v_cmp_ge_f32_e64 s[0:1], 0, v182
	v_add_u32_e32 v182, 1, v180
	s_nop 0
	v_cndmask_b32_e64 v181, v180, v181, s[0:1]
	v_fma_f32 v180, -v182, v180, v138
	v_cmp_lt_f32_e64 s[0:1], 0, v180
	s_nop 1
	v_cndmask_b32_e64 v180, v181, v182, s[0:1]
	v_mul_f32_e32 v181, 0x37800000, v180
	v_cndmask_b32_e32 v180, v180, v181, vcc
	v_cmp_class_f32_e32 vcc, v138, v206
	s_nop 1
	v_cndmask_b32_e32 v138, v180, v138, vcc
	v_rcp_f32_e32 v138, v138
	s_nop 0
	v_pk_mul_f32 v[106:107], v[106:107], v[138:139] op_sel_hi:[1,0]
	s_nop 0
	v_pk_mul_f32 v[106:107], v[0:1], v[106:107]
	s_nop 0
	v_cvt_pk_bf16_f32 v106, v106, v107
	global_store_dword v[12:13], v106, off
	v_fmamk_f32 v140, v140, 0x3c000000, v205
	v_cmp_gt_f32_e32 vcc, s63, v140
	v_mul_f32_e32 v180, 0x4f800000, v140
	s_nop 0
	v_cndmask_b32_e32 v140, v140, v180, vcc
	v_sqrt_f32_e32 v180, v140
	s_nop 0
	v_add_u32_e32 v181, -1, v180
	v_fma_f32 v182, -v181, v180, v140
	v_cmp_ge_f32_e64 s[0:1], 0, v182
	v_add_u32_e32 v182, 1, v180
	s_nop 0
	v_cndmask_b32_e64 v181, v180, v181, s[0:1]
	v_fma_f32 v180, -v182, v180, v140
	v_cmp_lt_f32_e64 s[0:1], 0, v180
	s_nop 1
	v_cndmask_b32_e64 v180, v181, v182, s[0:1]
	v_mul_f32_e32 v181, 0x37800000, v180
	v_cndmask_b32_e32 v180, v180, v181, vcc
	v_cmp_class_f32_e32 vcc, v140, v206
	s_nop 1
	v_cndmask_b32_e32 v140, v180, v140, vcc
	v_rcp_f32_e32 v140, v140
	s_nop 0
	v_pk_mul_f32 v[108:109], v[108:109], v[140:141] op_sel_hi:[1,0]
	s_nop 0
	v_pk_mul_f32 v[108:109], v[0:1], v[108:109]
	s_nop 0
	v_cvt_pk_bf16_f32 v108, v108, v109
	global_store_dword v[10:11], v108, off
	v_fmamk_f32 v142, v142, 0x3c000000, v205
	v_cmp_gt_f32_e32 vcc, s63, v142
	v_mul_f32_e32 v180, 0x4f800000, v142
	s_nop 0
	v_cndmask_b32_e32 v142, v142, v180, vcc
	v_sqrt_f32_e32 v180, v142
	s_nop 0
	v_add_u32_e32 v181, -1, v180
	v_fma_f32 v182, -v181, v180, v142
	v_cmp_ge_f32_e64 s[0:1], 0, v182
	v_add_u32_e32 v182, 1, v180
	s_nop 0
	v_cndmask_b32_e64 v181, v180, v181, s[0:1]
	v_fma_f32 v180, -v182, v180, v142
	v_cmp_lt_f32_e64 s[0:1], 0, v180
	s_nop 1
	v_cndmask_b32_e64 v180, v181, v182, s[0:1]
	v_mul_f32_e32 v181, 0x37800000, v180
	v_cndmask_b32_e32 v180, v180, v181, vcc
	v_cmp_class_f32_e32 vcc, v142, v206
	s_nop 1
	v_cndmask_b32_e32 v142, v180, v142, vcc
	v_rcp_f32_e32 v142, v142
	s_nop 0
	v_pk_mul_f32 v[110:111], v[110:111], v[142:143] op_sel_hi:[1,0]
	s_nop 0
	v_pk_mul_f32 v[110:111], v[0:1], v[110:111]
	s_nop 0
	v_cvt_pk_bf16_f32 v110, v110, v111
	global_store_dword v[8:9], v110, off
	s_mov_b64 s[0:1], 16
	s_and_b64 vcc, exec, s[2:3]
	s_mov_b64 s[2:3], 0
	s_cbranch_vccnz .LBB0_557
	s_mov_b32 s2, 64
	s_mov_b64 s[0:1], 0
	s_and_b64 vcc, exec, s[20:21]
	s_cbranch_vccz .LBB0_515
	s_bfe_u32 s0, s87, 0x40002
	s_lshl_b32 s1, s0, 6
	s_lshl_b32 s0, s0, 7
	v_readlane_b32 s2, v246, 4
	v_readlane_b32 s3, v246, 5
	s_add_u32 s12, s2, s0
	s_addc_u32 s13, s3, 0
	v_readlane_b32 s2, v246, 10
	v_readlane_b32 s3, v246, 11
	s_add_u32 s14, s2, s1
	s_addc_u32 s15, s3, 0
	v_readlane_b32 s1, v246, 8
	s_add_u32 s16, s1, s0
	v_readlane_b32 s1, v246, 9
	s_addc_u32 s17, s1, 0
	v_readlane_b32 s1, v246, 6
	s_add_u32 s18, s1, s0
	v_readlane_b32 s1, v246, 7
	s_addc_u32 s19, s1, 0
	v_readlane_b32 s1, v246, 14
	s_add_u32 s42, s1, s0
	v_readlane_b32 s1, v246, 16
	s_addc_u32 s43, s1, 0
	v_readlane_b32 s1, v246, 18
	s_add_u32 s44, s1, s0
	v_readlane_b32 s0, v246, 19
	s_addc_u32 s45, s0, 0
	v_readlane_b32 s0, v247, 36
	s_mov_b32 s46, 0
	s_mov_b32 s86, s0
	v_readlane_b32 s1, v247, 37
	s_branch .LBB0_561
